# ret_output gated epilogue: the 8 in-place gate loads of each row group issued together instead of load-wait-store serially; NA split 512
# speedup vs baseline: 1.0098x; 1.0098x over previous
; __device__ __forceinline__ unsigned cvt_pk_bf16(float lo, float hi) { unsigned r; asm("v_cvt_pk_bf16_f32 %0, %1, %2" : "=v"(r) : "v"(lo), "v"(hi)); return r; }
; __device__ __forceinline__ float ret_lg(int h) { return logf(1.0f - exp2f(-5.0f - (float)h)); }
; __device__ void ret_output(const Params& p, unsigned char* shm, int wg, int nwg) {
;     ...
;     for (int item = wg; item < BATCH * 128 * 6; item += nwg) {
;         const int h = item % 6, c = (item / 6) % 128, b = item / 768;
;         const float lg = ret_lg(h);
; #pragma unroll
;         for (int it = 0; it < 4; ++it) { const int idx = it * NTHR + tid, tok = idx >> 4, ch8 = idx & 15;
;             const bf16_t* zr = Z + (size_t)(b * T + c * 128 + tok) * ZLD + ZC_RET + h * 128 + ch8 * 8;
;             const u32x4 q4 = *(const u32x4*)(zr); const u32x4 k4 = *(const u32x4*)(zr + 768); const u32x4 v4 = *(const u32x4*)(zr + 1536);
;             const unsigned vv[4] = {v4.x, v4.y, v4.z, v4.w};
; #pragma unroll
;             for (int e = 0; e < 4; ++e) { *(bf16_t*)(Vt + (ch8 * 8 + 2 * e) * RLD + tok * 2) = (bf16_t)(vv[e] & 0xffffu); *(bf16_t*)(Vt + (ch8 * 8 + 2 * e + 1) * RLD + tok * 2) = (bf16_t)(vv[e] >> 16); }
;             const f32x4* rt = (const f32x4*)(p.ws + WS_ROT) + ((size_t)(c * 128 + tok) * 64 + ch8 * 4) / 2; const f32x4 cs01 = rt[0], cs23 = rt[1];
;             float qr[8], kr[8]; rot8(q4, cs01, cs23, qr); rot8(k4, cs01, cs23, kr);
;             u32x4 qo, ko;
;             qo.x = cvt_pk_bf16(qr[0], qr[1]); qo.y = cvt_pk_bf16(qr[2], qr[3]); qo.z = cvt_pk_bf16(qr[4], qr[5]); qo.w = cvt_pk_bf16(qr[6], qr[7]);
;             const float sc = 0.08838834764831845f;
;             ko.x = cvt_pk_bf16(kr[0] * sc, kr[1] * sc); ko.y = cvt_pk_bf16(kr[2] * sc, kr[3] * sc); ko.z = cvt_pk_bf16(kr[4] * sc, kr[5] * sc); ko.w = cvt_pk_bf16(kr[6] * sc, kr[7] * sc);
;             *(u32x4*)(Qs + tok * RLD + ch8 * 16) = qo; *(u32x4*)(Ks + tok * RLD + ch8 * 16) = ko;
;         }
.LBB0_135:
	s_mul_hi_i32 s0, s2, 0x2aaaaaab
	s_lshr_b32 s1, s0, 31
	s_add_i32 s4, s0, s1
	s_mul_i32 s3, s4, -6
	s_add_i32 s3, s2, s3
	v_cvt_f32_i32_e32 v2, s3
	s_ashr_i32 s5, s4, 31
	s_lshr_b32 s5, s5, 25
	s_add_i32 s5, s4, s5
	v_sub_f32_e32 v2, 0xc0a00000, v2
	v_cmp_gt_f32_e32 vcc, s53, v2
	s_and_b32 s5, s5, 0x1ffff80
	s_lshr_b32 s0, s0, 7
	v_cndmask_b32_e32 v3, 0, v168, vcc
	v_add_f32_e32 v2, v2, v3
	v_exp_f32_e32 v2, v2
	s_sub_i32 s5, s4, s5
	s_add_i32 s6, s0, s1
	s_and_b64 s[0:1], vcc, exec
	s_cselect_b32 s0, 0xffffffc0, 0
	v_ldexp_f32 v2, v2, s0
	s_lshl_b32 s0, s6, 14
	s_lshl_b32 s3, s5, 7
	s_add_i32 s12, s3, s0
	s_mulk_i32 s4, 0xfd00
	s_add_i32 s0, s10, s4
	v_add_u32_e32 v3, s12, v72
	v_mov_b64_e32 v[52:53], s[78:79]
	s_ashr_i32 s1, s0, 31
	v_mad_i64_i32 v[4:5], s[4:5], v3, s22, v[52:53]
	s_lshl_b64 s[4:5], s[0:1], 1
	s_nop 0
	v_lshl_add_u64 v[4:5], v[4:5], 0, s[4:5]
	v_lshl_add_u64 v[4:5], v[4:5], 0, v[0:1]
	v_lshl_add_u64 v[12:13], v[4:5], 0, s[20:21]
	v_add_co_u32_e32 v4, vcc, s16, v4
	v_add_u32_e32 v152, v55, v73
	s_nop 0
	v_addc_co_u32_e32 v5, vcc, 0, v5, vcc
	global_load_dwordx4 v[4:7], v[4:5], off offset:256
	s_nop 0
	global_load_dwordx4 v[8:11], v[12:13], off offset:1536
	s_nop 0
	global_load_dwordx4 v[12:15], v[12:13], off offset:3072
	v_add_u32_e32 v153, v55, v75
	v_add_u32_e32 v154, v55, v77
	v_sub_f32_e32 v2, 1.0, v2
	v_add_u32_e32 v155, v55, v79
	v_add_u32_e32 v179, v57, v56
	v_add_u32_e32 v180, v57, v58
	v_add_u32_e32 v181, v57, v59
	v_add_u32_e32 v182, v64, v59
	v_add_u32_e32 v183, v67, v61
	s_waitcnt vmcnt(0)
	ds_write_b16 v120, v12
	ds_write_b16_d16_hi v120, v12 offset:272
	ds_write_b16 v120, v13 offset:544
	ds_write_b16_d16_hi v120, v13 offset:816
	ds_write_b16 v120, v14 offset:1088
	ds_write_b16_d16_hi v120, v14 offset:1360
	ds_write_b16 v120, v15 offset:1632
	ds_write_b16_d16_hi v120, v15 offset:1904
	v_add_u32_e32 v12, s3, v72
	v_ashrrev_i32_e32 v13, 31, v12
	v_lshlrev_b64 v[12:13], 9, v[12:13]
	v_or_b32_e32 v12, v12, v121
	v_lshl_add_u64 v[16:17], s[14:15], 0, v[12:13]
	global_load_dwordx4 v[12:15], v[16:17], off offset:16
	s_nop 0
	global_load_dwordx4 v[16:19], v[16:17], off
	v_lshlrev_b32_e32 v20, 16, v4
	v_and_b32_e32 v21, 0xffff0000, v4
	v_lshlrev_b32_e32 v4, 16, v5
	v_and_b32_e32 v5, 0xffff0000, v5
	s_waitcnt vmcnt(0)
	v_pk_mul_f32 v[22:23], v[16:17], v[20:21]
	v_pk_mul_f32 v[20:21], v[16:17], v[20:21] op_sel:[1,0] op_sel_hi:[0,1]
	v_sub_f32_e32 v3, v22, v23
	v_add_f32_e32 v22, v20, v21
	v_pk_mul_f32 v[20:21], v[18:19], v[4:5]
	v_pk_mul_f32 v[4:5], v[18:19], v[4:5] op_sel:[1,0] op_sel_hi:[0,1]
	v_add_f32_e32 v24, v4, v5
	v_lshlrev_b32_e32 v4, 16, v6
	v_and_b32_e32 v5, 0xffff0000, v6
	v_sub_f32_e32 v23, v20, v21
	v_pk_mul_f32 v[20:21], v[12:13], v[4:5]
	v_pk_mul_f32 v[4:5], v[12:13], v[4:5] op_sel:[1,0] op_sel_hi:[0,1]
	v_sub_f32_e32 v20, v20, v21
	v_add_f32_e32 v21, v4, v5
	v_lshlrev_b32_e32 v4, 16, v7
	v_and_b32_e32 v5, 0xffff0000, v7
	v_pk_mul_f32 v[6:7], v[14:15], v[4:5]
	v_pk_mul_f32 v[4:5], v[14:15], v[4:5] op_sel:[1,0] op_sel_hi:[0,1]
	v_add_f32_e32 v26, v4, v5
	v_lshlrev_b32_e32 v4, 16, v8
	v_and_b32_e32 v5, 0xffff0000, v8
	v_sub_f32_e32 v25, v6, v7
	v_pk_mul_f32 v[6:7], v[16:17], v[4:5]
	v_pk_mul_f32 v[4:5], v[16:17], v[4:5] op_sel:[1,0] op_sel_hi:[0,1]
	v_add_f32_e32 v16, v4, v5
	v_lshlrev_b32_e32 v4, 16, v9
	v_and_b32_e32 v5, 0xffff0000, v9
	v_sub_f32_e32 v8, v6, v7
	v_pk_mul_f32 v[6:7], v[18:19], v[4:5]
	v_pk_mul_f32 v[4:5], v[18:19], v[4:5] op_sel:[1,0] op_sel_hi:[0,1]
	v_add_f32_e32 v17, v4, v5
	v_lshlrev_b32_e32 v4, 16, v10
	v_and_b32_e32 v5, 0xffff0000, v10
	v_sub_f32_e32 v9, v6, v7
	v_pk_mul_f32 v[6:7], v[12:13], v[4:5]
	v_pk_mul_f32 v[4:5], v[12:13], v[4:5] op_sel:[1,0] op_sel_hi:[0,1]
	v_add_f32_e32 v12, v4, v5
	v_lshlrev_b32_e32 v4, 16, v11
	v_and_b32_e32 v5, 0xffff0000, v11
	v_sub_f32_e32 v10, v6, v7
	v_pk_mul_f32 v[6:7], v[14:15], v[4:5]
	v_pk_mul_f32 v[4:5], v[14:15], v[4:5] op_sel:[1,0] op_sel_hi:[0,1]
	v_add_f32_e32 v13, v4, v5
	v_cvt_pk_bf16_f32 v4, v3, v22
	v_mul_f32_e32 v3, 0x3db504f3, v8
	v_mul_f32_e32 v8, 0x3db504f3, v16
	v_cvt_pk_bf16_f32 v8, v3, v8
	v_mul_f32_e32 v3, 0x3db504f3, v9
	v_mul_f32_e32 v9, 0x3db504f3, v17
	v_sub_f32_e32 v11, v6, v7
	v_cvt_pk_bf16_f32 v9, v3, v9
	v_mul_f32_e32 v3, 0x3db504f3, v10
	v_mul_f32_e32 v10, 0x3db504f3, v12
	v_cvt_pk_bf16_f32 v10, v3, v10
	v_mul_f32_e32 v3, 0x3db504f3, v11
	v_mul_f32_e32 v11, 0x3db504f3, v13
	v_cvt_pk_bf16_f32 v5, v23, v24
	v_cvt_pk_bf16_f32 v6, v20, v21
	v_cvt_pk_bf16_f32 v7, v25, v26
	v_cvt_pk_bf16_f32 v11, v3, v11
	v_add_u32_e32 v3, v54, v73
	ds_write_b128 v3, v[4:7]
	ds_write_b128 v3, v[8:11] offset:34816
	v_add_u32_e32 v3, s12, v74
	v_mad_i64_i32 v[4:5], s[0:1], v3, s22, v[52:53]
	v_lshl_add_u64 v[4:5], v[4:5], 0, s[4:5]
	v_lshl_add_u64 v[4:5], v[4:5], 0, v[0:1]
	v_lshl_add_u64 v[12:13], v[4:5], 0, s[20:21]
	v_add_co_u32_e32 v4, vcc, s16, v4
	s_nop 1
	v_addc_co_u32_e32 v5, vcc, 0, v5, vcc
	global_load_dwordx4 v[4:7], v[4:5], off offset:256
	s_nop 0
	global_load_dwordx4 v[8:11], v[12:13], off offset:1536
	s_nop 0
	global_load_dwordx4 v[12:15], v[12:13], off offset:3072
	s_waitcnt vmcnt(0)
	ds_write_b16 v122, v12
	ds_write_b16_d16_hi v122, v12 offset:272
	ds_write_b16 v122, v13 offset:544
	ds_write_b16_d16_hi v122, v13 offset:816
	ds_write_b16 v122, v14 offset:1088
	ds_write_b16_d16_hi v122, v14 offset:1360
	ds_write_b16 v122, v15 offset:1632
	ds_write_b16_d16_hi v122, v15 offset:1904
	v_add_u32_e32 v12, s3, v74
	v_ashrrev_i32_e32 v13, 31, v12
	v_lshlrev_b64 v[12:13], 9, v[12:13]
	v_or_b32_e32 v12, v12, v121
	v_lshl_add_u64 v[16:17], s[14:15], 0, v[12:13]
	global_load_dwordx4 v[12:15], v[16:17], off offset:16
	s_nop 0
	global_load_dwordx4 v[16:19], v[16:17], off
	v_lshlrev_b32_e32 v20, 16, v4
	v_and_b32_e32 v21, 0xffff0000, v4
	v_lshlrev_b32_e32 v4, 16, v5
	v_and_b32_e32 v5, 0xffff0000, v5
	s_waitcnt vmcnt(0)
; __device__ __forceinline__ unsigned cvt_pk_bf16(float lo, float hi) { unsigned r; asm("v_cvt_pk_bf16_f32 %0, %1, %2" : "=v"(r) : "v"(lo), "v"(hi)); return r; }
; __device__ void ret_output(const Params& p, unsigned char* shm, int wg, int nwg) {
;     ...
;         for (int it = 0; it < 4; ++it) { const int idx = it * NTHR + tid, tok = idx >> 4, ch8 = idx & 15;
;             const bf16_t* zr = Z + (size_t)(b * T + c * 128 + tok) * ZLD + ZC_RET + h * 128 + ch8 * 8;
;             const u32x4 q4 = *(const u32x4*)(zr); const u32x4 k4 = *(const u32x4*)(zr + 768); const u32x4 v4 = *(const u32x4*)(zr + 1536);
;             const unsigned vv[4] = {v4.x, v4.y, v4.z, v4.w};
; #pragma unroll
;             for (int e = 0; e < 4; ++e) { *(bf16_t*)(Vt + (ch8 * 8 + 2 * e) * RLD + tok * 2) = (bf16_t)(vv[e] & 0xffffu); *(bf16_t*)(Vt + (ch8 * 8 + 2 * e + 1) * RLD + tok * 2) = (bf16_t)(vv[e] >> 16); }
;             const f32x4* rt = (const f32x4*)(p.ws + WS_ROT) + ((size_t)(c * 128 + tok) * 64 + ch8 * 4) / 2; const f32x4 cs01 = rt[0], cs23 = rt[1];
;             float qr[8], kr[8]; rot8(q4, cs01, cs23, qr); rot8(k4, cs01, cs23, kr);
;             u32x4 qo, ko;
;             qo.x = cvt_pk_bf16(qr[0], qr[1]); qo.y = cvt_pk_bf16(qr[2], qr[3]); qo.z = cvt_pk_bf16(qr[4], qr[5]); qo.w = cvt_pk_bf16(qr[6], qr[7]);
;             const float sc = 0.08838834764831845f;
;             ko.x = cvt_pk_bf16(kr[0] * sc, kr[1] * sc); ko.y = cvt_pk_bf16(kr[2] * sc, kr[3] * sc); ko.z = cvt_pk_bf16(kr[4] * sc, kr[5] * sc); ko.w = cvt_pk_bf16(kr[6] * sc, kr[7] * sc);
;             *(u32x4*)(Qs + tok * RLD + ch8 * 16) = qo; *(u32x4*)(Ks + tok * RLD + ch8 * 16) = ko;
;         }
	v_pk_mul_f32 v[22:23], v[16:17], v[20:21]
	v_pk_mul_f32 v[20:21], v[16:17], v[20:21] op_sel:[1,0] op_sel_hi:[0,1]
	v_sub_f32_e32 v3, v22, v23
	v_add_f32_e32 v22, v20, v21
	v_pk_mul_f32 v[20:21], v[18:19], v[4:5]
	v_pk_mul_f32 v[4:5], v[18:19], v[4:5] op_sel:[1,0] op_sel_hi:[0,1]
	v_add_f32_e32 v24, v4, v5
	v_lshlrev_b32_e32 v4, 16, v6
	v_and_b32_e32 v5, 0xffff0000, v6
	v_sub_f32_e32 v23, v20, v21
	v_pk_mul_f32 v[20:21], v[12:13], v[4:5]
	v_pk_mul_f32 v[4:5], v[12:13], v[4:5] op_sel:[1,0] op_sel_hi:[0,1]
	v_sub_f32_e32 v20, v20, v21
	v_add_f32_e32 v21, v4, v5
	v_lshlrev_b32_e32 v4, 16, v7
	v_and_b32_e32 v5, 0xffff0000, v7
	v_pk_mul_f32 v[6:7], v[14:15], v[4:5]
	v_pk_mul_f32 v[4:5], v[14:15], v[4:5] op_sel:[1,0] op_sel_hi:[0,1]
	v_add_f32_e32 v26, v4, v5
	v_lshlrev_b32_e32 v4, 16, v8
	v_and_b32_e32 v5, 0xffff0000, v8
	v_sub_f32_e32 v25, v6, v7
	v_pk_mul_f32 v[6:7], v[16:17], v[4:5]
	v_pk_mul_f32 v[4:5], v[16:17], v[4:5] op_sel:[1,0] op_sel_hi:[0,1]
	v_add_f32_e32 v16, v4, v5
	v_lshlrev_b32_e32 v4, 16, v9
	v_and_b32_e32 v5, 0xffff0000, v9
	v_sub_f32_e32 v8, v6, v7
	v_pk_mul_f32 v[6:7], v[18:19], v[4:5]
	v_pk_mul_f32 v[4:5], v[18:19], v[4:5] op_sel:[1,0] op_sel_hi:[0,1]
	v_add_f32_e32 v17, v4, v5
	v_lshlrev_b32_e32 v4, 16, v10
	v_and_b32_e32 v5, 0xffff0000, v10
	v_sub_f32_e32 v9, v6, v7
	v_pk_mul_f32 v[6:7], v[12:13], v[4:5]
	v_pk_mul_f32 v[4:5], v[12:13], v[4:5] op_sel:[1,0] op_sel_hi:[0,1]
	v_add_f32_e32 v12, v4, v5
	v_lshlrev_b32_e32 v4, 16, v11
	v_and_b32_e32 v5, 0xffff0000, v11
	v_sub_f32_e32 v10, v6, v7
	v_pk_mul_f32 v[6:7], v[14:15], v[4:5]
	v_pk_mul_f32 v[4:5], v[14:15], v[4:5] op_sel:[1,0] op_sel_hi:[0,1]
	v_add_f32_e32 v13, v4, v5
	v_cvt_pk_bf16_f32 v4, v3, v22
	v_mul_f32_e32 v3, 0x3db504f3, v8
	v_mul_f32_e32 v8, 0x3db504f3, v16
	v_cvt_pk_bf16_f32 v8, v3, v8
	v_mul_f32_e32 v3, 0x3db504f3, v9
	v_mul_f32_e32 v9, 0x3db504f3, v17
	v_sub_f32_e32 v11, v6, v7
	v_cvt_pk_bf16_f32 v9, v3, v9
	v_mul_f32_e32 v3, 0x3db504f3, v10
	v_mul_f32_e32 v10, 0x3db504f3, v12
	v_cvt_pk_bf16_f32 v10, v3, v10
	v_mul_f32_e32 v3, 0x3db504f3, v11
	v_mul_f32_e32 v11, 0x3db504f3, v13
	v_cvt_pk_bf16_f32 v5, v23, v24
	v_cvt_pk_bf16_f32 v6, v20, v21
	v_cvt_pk_bf16_f32 v7, v25, v26
	v_cvt_pk_bf16_f32 v11, v3, v11
	v_add_u32_e32 v3, v54, v75
	ds_write_b128 v3, v[4:7]
	ds_write_b128 v3, v[8:11] offset:34816
	v_add_u32_e32 v3, s12, v76
	v_mad_i64_i32 v[4:5], s[0:1], v3, s22, v[52:53]
	v_lshl_add_u64 v[4:5], v[4:5], 0, s[4:5]
	v_lshl_add_u64 v[4:5], v[4:5], 0, v[0:1]
	v_lshl_add_u64 v[12:13], v[4:5], 0, s[20:21]
	v_add_co_u32_e32 v4, vcc, s16, v4
	s_nop 1
	v_addc_co_u32_e32 v5, vcc, 0, v5, vcc
	global_load_dwordx4 v[4:7], v[4:5], off offset:256
	s_nop 0
	global_load_dwordx4 v[8:11], v[12:13], off offset:1536
	s_nop 0
	global_load_dwordx4 v[12:15], v[12:13], off offset:3072
	s_waitcnt vmcnt(0)
	ds_write_b16 v123, v12
	ds_write_b16_d16_hi v123, v12 offset:272
	ds_write_b16 v123, v13 offset:544
	ds_write_b16_d16_hi v123, v13 offset:816
	ds_write_b16 v123, v14 offset:1088
	ds_write_b16_d16_hi v123, v14 offset:1360
	ds_write_b16 v123, v15 offset:1632
	ds_write_b16_d16_hi v123, v15 offset:1904
	v_add_u32_e32 v12, s3, v76
	v_ashrrev_i32_e32 v13, 31, v12
	v_lshlrev_b64 v[12:13], 9, v[12:13]
	v_or_b32_e32 v12, v12, v121
	v_lshl_add_u64 v[16:17], s[14:15], 0, v[12:13]
	global_load_dwordx4 v[12:15], v[16:17], off offset:16
	s_nop 0
	global_load_dwordx4 v[16:19], v[16:17], off
	v_lshlrev_b32_e32 v20, 16, v4
	v_and_b32_e32 v21, 0xffff0000, v4
	v_lshlrev_b32_e32 v4, 16, v5
	v_and_b32_e32 v5, 0xffff0000, v5
	s_waitcnt vmcnt(0)
	v_pk_mul_f32 v[22:23], v[16:17], v[20:21]
	v_pk_mul_f32 v[20:21], v[16:17], v[20:21] op_sel:[1,0] op_sel_hi:[0,1]
	v_sub_f32_e32 v3, v22, v23
	v_add_f32_e32 v22, v20, v21
	v_pk_mul_f32 v[20:21], v[18:19], v[4:5]
	v_pk_mul_f32 v[4:5], v[18:19], v[4:5] op_sel:[1,0] op_sel_hi:[0,1]
	v_add_f32_e32 v24, v4, v5
	v_lshlrev_b32_e32 v4, 16, v6
	v_and_b32_e32 v5, 0xffff0000, v6
	v_sub_f32_e32 v23, v20, v21
	v_pk_mul_f32 v[20:21], v[12:13], v[4:5]
	v_pk_mul_f32 v[4:5], v[12:13], v[4:5] op_sel:[1,0] op_sel_hi:[0,1]
	v_sub_f32_e32 v20, v20, v21
	v_add_f32_e32 v21, v4, v5
	v_lshlrev_b32_e32 v4, 16, v7
	v_and_b32_e32 v5, 0xffff0000, v7
	v_pk_mul_f32 v[6:7], v[14:15], v[4:5]
	v_pk_mul_f32 v[4:5], v[14:15], v[4:5] op_sel:[1,0] op_sel_hi:[0,1]
	v_add_f32_e32 v26, v4, v5
	v_lshlrev_b32_e32 v4, 16, v8
	v_and_b32_e32 v5, 0xffff0000, v8
	v_sub_f32_e32 v25, v6, v7
	v_pk_mul_f32 v[6:7], v[16:17], v[4:5]
	v_pk_mul_f32 v[4:5], v[16:17], v[4:5] op_sel:[1,0] op_sel_hi:[0,1]
	v_add_f32_e32 v16, v4, v5
	v_lshlrev_b32_e32 v4, 16, v9
	v_and_b32_e32 v5, 0xffff0000, v9
	v_sub_f32_e32 v8, v6, v7
	v_pk_mul_f32 v[6:7], v[18:19], v[4:5]
	v_pk_mul_f32 v[4:5], v[18:19], v[4:5] op_sel:[1,0] op_sel_hi:[0,1]
	v_add_f32_e32 v17, v4, v5
	v_lshlrev_b32_e32 v4, 16, v10
	v_and_b32_e32 v5, 0xffff0000, v10
	v_sub_f32_e32 v9, v6, v7
	v_pk_mul_f32 v[6:7], v[12:13], v[4:5]
	v_pk_mul_f32 v[4:5], v[12:13], v[4:5] op_sel:[1,0] op_sel_hi:[0,1]
	v_add_f32_e32 v12, v4, v5
	v_lshlrev_b32_e32 v4, 16, v11
	v_and_b32_e32 v5, 0xffff0000, v11
	v_sub_f32_e32 v10, v6, v7
	v_pk_mul_f32 v[6:7], v[14:15], v[4:5]
	v_pk_mul_f32 v[4:5], v[14:15], v[4:5] op_sel:[1,0] op_sel_hi:[0,1]
	v_add_f32_e32 v13, v4, v5
	v_cvt_pk_bf16_f32 v4, v3, v22
	v_mul_f32_e32 v3, 0x3db504f3, v8
	v_mul_f32_e32 v8, 0x3db504f3, v16
	v_cvt_pk_bf16_f32 v8, v3, v8
	v_mul_f32_e32 v3, 0x3db504f3, v9
	v_mul_f32_e32 v9, 0x3db504f3, v17
	v_sub_f32_e32 v11, v6, v7
	v_cvt_pk_bf16_f32 v9, v3, v9
	v_mul_f32_e32 v3, 0x3db504f3, v10
	v_mul_f32_e32 v10, 0x3db504f3, v12
	v_cvt_pk_bf16_f32 v10, v3, v10
	v_mul_f32_e32 v3, 0x3db504f3, v11
	v_mul_f32_e32 v11, 0x3db504f3, v13
	v_cvt_pk_bf16_f32 v5, v23, v24
	v_cvt_pk_bf16_f32 v6, v20, v21
	v_cvt_pk_bf16_f32 v7, v25, v26
	v_cvt_pk_bf16_f32 v11, v3, v11
	v_add_u32_e32 v3, v54, v77
	ds_write_b128 v3, v[4:7]
	ds_write_b128 v3, v[8:11] offset:34816
	v_add_u32_e32 v3, s12, v78
	v_mad_i64_i32 v[4:5], s[0:1], v3, s22, v[52:53]
	v_lshl_add_u64 v[4:5], v[4:5], 0, s[4:5]
	v_lshl_add_u64 v[4:5], v[4:5], 0, v[0:1]
	v_lshl_add_u64 v[12:13], v[4:5], 0, s[20:21]
	v_add_co_u32_e32 v4, vcc, s16, v4
	s_nop 1
	v_addc_co_u32_e32 v5, vcc, 0, v5, vcc
	global_load_dwordx4 v[4:7], v[4:5], off offset:256
	s_nop 0
	global_load_dwordx4 v[8:11], v[12:13], off offset:1536
	s_nop 0
	global_load_dwordx4 v[12:15], v[12:13], off offset:3072
	s_waitcnt vmcnt(0)
; __device__ __forceinline__ unsigned cvt_pk_bf16(float lo, float hi) { unsigned r; asm("v_cvt_pk_bf16_f32 %0, %1, %2" : "=v"(r) : "v"(lo), "v"(hi)); return r; }
; __device__ __forceinline__ float ret_lg(int h) { return logf(1.0f - exp2f(-5.0f - (float)h)); }
; __device__ void ret_output(const Params& p, unsigned char* shm, int wg, int nwg) {
;     ...
;         const float lg = ret_lg(h);
; #pragma unroll
;         for (int it = 0; it < 4; ++it) { const int idx = it * NTHR + tid, tok = idx >> 4, ch8 = idx & 15;
;             const bf16_t* zr = Z + (size_t)(b * T + c * 128 + tok) * ZLD + ZC_RET + h * 128 + ch8 * 8;
;             const u32x4 q4 = *(const u32x4*)(zr); const u32x4 k4 = *(const u32x4*)(zr + 768); const u32x4 v4 = *(const u32x4*)(zr + 1536);
;             const unsigned vv[4] = {v4.x, v4.y, v4.z, v4.w};
; #pragma unroll
;             for (int e = 0; e < 4; ++e) { *(bf16_t*)(Vt + (ch8 * 8 + 2 * e) * RLD + tok * 2) = (bf16_t)(vv[e] & 0xffffu); *(bf16_t*)(Vt + (ch8 * 8 + 2 * e + 1) * RLD + tok * 2) = (bf16_t)(vv[e] >> 16); }
;             const f32x4* rt = (const f32x4*)(p.ws + WS_ROT) + ((size_t)(c * 128 + tok) * 64 + ch8 * 4) / 2; const f32x4 cs01 = rt[0], cs23 = rt[1];
;             float qr[8], kr[8]; rot8(q4, cs01, cs23, qr); rot8(k4, cs01, cs23, kr);
;             u32x4 qo, ko;
;             qo.x = cvt_pk_bf16(qr[0], qr[1]); qo.y = cvt_pk_bf16(qr[2], qr[3]); qo.z = cvt_pk_bf16(qr[4], qr[5]); qo.w = cvt_pk_bf16(qr[6], qr[7]);
;             const float sc = 0.08838834764831845f;
;             ko.x = cvt_pk_bf16(kr[0] * sc, kr[1] * sc); ko.y = cvt_pk_bf16(kr[2] * sc, kr[3] * sc); ko.z = cvt_pk_bf16(kr[4] * sc, kr[5] * sc); ko.w = cvt_pk_bf16(kr[6] * sc, kr[7] * sc);
;             *(u32x4*)(Qs + tok * RLD + ch8 * 16) = qo; *(u32x4*)(Ks + tok * RLD + ch8 * 16) = ko;
;         }
;         { const float* src = StF + (size_t)item * 16384;
; #pragma unroll
;           for (int it = 0; it < 4; ++it) { const int idx = it * NTHR + tid, v = idx >> 4, ch8 = idx & 15; const f32x4 a = *(const f32x4*)(src + v * 128 + ch8 * 8), bq = *(const f32x4*)(src + v * 128 + ch8 * 8 + 4);
;               u32x4 o; o.x = cvt_pk_bf16(a[0], a[1]); o.y = cvt_pk_bf16(a[2], a[3]); o.z = cvt_pk_bf16(bq[0], bq[1]); o.w = cvt_pk_bf16(bq[2], bq[3]); *(u32x4*)(Rs + v * RLD + ch8 * 16) = o; } }
;         __syncthreads();
	ds_write_b16 v124, v12
	ds_write_b16_d16_hi v124, v12 offset:272
	ds_write_b16 v124, v13 offset:544
	ds_write_b16_d16_hi v124, v13 offset:816
	ds_write_b16 v124, v14 offset:1088
	ds_write_b16_d16_hi v124, v14 offset:1360
	ds_write_b16 v124, v15 offset:1632
	ds_write_b16_d16_hi v124, v15 offset:1904
	v_add_u32_e32 v12, s3, v78
	v_ashrrev_i32_e32 v13, 31, v12
	v_lshlrev_b64 v[12:13], 9, v[12:13]
	v_or_b32_e32 v12, v12, v121
	v_lshl_add_u64 v[16:17], s[14:15], 0, v[12:13]
	global_load_dwordx4 v[12:15], v[16:17], off offset:16
	s_nop 0
	global_load_dwordx4 v[16:19], v[16:17], off
	v_lshlrev_b32_e32 v20, 16, v4
	v_and_b32_e32 v21, 0xffff0000, v4
	v_lshlrev_b32_e32 v4, 16, v5
	v_and_b32_e32 v5, 0xffff0000, v5
	s_ashr_i32 s3, s2, 31
	s_lshl_b64 s[6:7], s[2:3], 16
	v_cmp_gt_f32_e32 vcc, s13, v2
	s_and_b64 s[0:1], vcc, exec
	s_cselect_b32 s0, 32, 0
	v_ldexp_f32 v2, v2, s0
	v_log_f32_e32 v2, v2
	v_lshl_add_u64 v[192:193], v[40:41], 0, s[6:7]
	s_add_i32 s2, s2, s54
	s_add_i32 s10, s10, s11
	v_cmp_lt_f32_e64 s[0:1], |v2|, s18
	s_cmpk_lt_i32 s2, 0x600
	s_waitcnt vmcnt(0)
	v_pk_mul_f32 v[22:23], v[16:17], v[20:21]
	v_pk_mul_f32 v[20:21], v[16:17], v[20:21] op_sel:[1,0] op_sel_hi:[0,1]
	v_sub_f32_e32 v3, v22, v23
	v_add_f32_e32 v22, v20, v21
	v_pk_mul_f32 v[20:21], v[18:19], v[4:5]
	v_pk_mul_f32 v[4:5], v[18:19], v[4:5] op_sel:[1,0] op_sel_hi:[0,1]
	v_add_f32_e32 v24, v4, v5
	v_lshlrev_b32_e32 v4, 16, v6
	v_and_b32_e32 v5, 0xffff0000, v6
	v_sub_f32_e32 v23, v20, v21
	v_pk_mul_f32 v[20:21], v[12:13], v[4:5]
	v_pk_mul_f32 v[4:5], v[12:13], v[4:5] op_sel:[1,0] op_sel_hi:[0,1]
	v_sub_f32_e32 v20, v20, v21
	v_add_f32_e32 v21, v4, v5
	v_lshlrev_b32_e32 v4, 16, v7
	v_and_b32_e32 v5, 0xffff0000, v7
	v_pk_mul_f32 v[6:7], v[14:15], v[4:5]
	v_pk_mul_f32 v[4:5], v[14:15], v[4:5] op_sel:[1,0] op_sel_hi:[0,1]
	v_add_f32_e32 v26, v4, v5
	v_lshlrev_b32_e32 v4, 16, v8
	v_and_b32_e32 v5, 0xffff0000, v8
	v_sub_f32_e32 v25, v6, v7
	v_pk_mul_f32 v[6:7], v[16:17], v[4:5]
	v_pk_mul_f32 v[4:5], v[16:17], v[4:5] op_sel:[1,0] op_sel_hi:[0,1]
	v_add_f32_e32 v16, v4, v5
	v_lshlrev_b32_e32 v4, 16, v9
	v_and_b32_e32 v5, 0xffff0000, v9
	v_sub_f32_e32 v8, v6, v7
	v_pk_mul_f32 v[6:7], v[18:19], v[4:5]
	v_pk_mul_f32 v[4:5], v[18:19], v[4:5] op_sel:[1,0] op_sel_hi:[0,1]
	v_add_f32_e32 v17, v4, v5
	v_lshlrev_b32_e32 v4, 16, v10
	v_and_b32_e32 v5, 0xffff0000, v10
	v_sub_f32_e32 v9, v6, v7
	v_pk_mul_f32 v[6:7], v[12:13], v[4:5]
	v_pk_mul_f32 v[4:5], v[12:13], v[4:5] op_sel:[1,0] op_sel_hi:[0,1]
	v_add_f32_e32 v12, v4, v5
	v_lshlrev_b32_e32 v4, 16, v11
	v_and_b32_e32 v5, 0xffff0000, v11
	v_sub_f32_e32 v10, v6, v7
	v_pk_mul_f32 v[6:7], v[14:15], v[4:5]
	v_pk_mul_f32 v[4:5], v[14:15], v[4:5] op_sel:[1,0] op_sel_hi:[0,1]
	v_add_f32_e32 v13, v4, v5
	v_cvt_pk_bf16_f32 v4, v3, v22
	v_mul_f32_e32 v3, 0x3db504f3, v8
	v_mul_f32_e32 v8, 0x3db504f3, v16
	v_cvt_pk_bf16_f32 v8, v3, v8
	v_mul_f32_e32 v3, 0x3db504f3, v9
	v_mul_f32_e32 v9, 0x3db504f3, v17
	v_sub_f32_e32 v11, v6, v7
	v_cvt_pk_bf16_f32 v9, v3, v9
	v_mul_f32_e32 v3, 0x3db504f3, v10
	v_mul_f32_e32 v10, 0x3db504f3, v12
	v_cvt_pk_bf16_f32 v10, v3, v10
	v_mul_f32_e32 v3, 0x3db504f3, v11
	v_mul_f32_e32 v11, 0x3db504f3, v13
	v_cvt_pk_bf16_f32 v5, v23, v24
	v_cvt_pk_bf16_f32 v6, v20, v21
	v_cvt_pk_bf16_f32 v7, v25, v26
	v_cvt_pk_bf16_f32 v11, v3, v11
	v_add_u32_e32 v3, v54, v79
	v_lshl_add_u64 v[12:13], v[38:39], 0, s[6:7]
	ds_write_b128 v3, v[4:7]
	ds_write_b128 v3, v[8:11] offset:34816
	v_lshl_add_u64 v[8:9], v[12:13], 0, v[42:43]
	global_load_dwordx4 v[4:7], v[8:9], off offset:16
	s_nop 0
	global_load_dwordx4 v[8:11], v[8:9], off
	s_waitcnt vmcnt(0)
	v_cvt_pk_bf16_f32 v8, v8, v9
	v_cvt_pk_bf16_f32 v9, v10, v11
	v_cvt_pk_bf16_f32 v10, v4, v5
	v_cvt_pk_bf16_f32 v11, v6, v7
	ds_write_b128 v152, v[8:11]
	v_lshl_add_u64 v[8:9], v[12:13], 0, v[44:45]
	global_load_dwordx4 v[4:7], v[8:9], off offset:16
	s_nop 0
	global_load_dwordx4 v[8:11], v[8:9], off
	s_waitcnt vmcnt(0)
	v_cvt_pk_bf16_f32 v8, v8, v9
	v_cvt_pk_bf16_f32 v9, v10, v11
	v_cvt_pk_bf16_f32 v10, v4, v5
	v_cvt_pk_bf16_f32 v11, v6, v7
	ds_write_b128 v153, v[8:11]
	v_lshl_add_u64 v[8:9], v[12:13], 0, v[46:47]
	global_load_dwordx4 v[4:7], v[8:9], off offset:16
	s_nop 0
	global_load_dwordx4 v[8:11], v[8:9], off
	s_waitcnt vmcnt(0)
	v_cvt_pk_bf16_f32 v8, v8, v9
	v_cvt_pk_bf16_f32 v9, v10, v11
	v_cvt_pk_bf16_f32 v10, v4, v5
	v_cvt_pk_bf16_f32 v11, v6, v7
	ds_write_b128 v154, v[8:11]
	v_lshl_add_u64 v[8:9], v[12:13], 0, v[48:49]
	global_load_dwordx4 v[4:7], v[8:9], off offset:16
	s_nop 0
	global_load_dwordx4 v[8:11], v[8:9], off
	v_mul_f32_e32 v3, 0x3f317217, v2
	v_fma_f32 v3, v2, s17, -v3
	v_fmac_f32_e32 v3, 0x3377d1cf, v2
	v_fmac_f32_e32 v3, 0x3f317217, v2
	v_cndmask_b32_e64 v2, v2, v3, s[0:1]
	v_cndmask_b32_e32 v3, 0, v177, vcc
	s_waitcnt vmcnt(0)
	v_cvt_pk_bf16_f32 v8, v8, v9
	v_cvt_pk_bf16_f32 v9, v10, v11
	v_cvt_pk_bf16_f32 v10, v4, v5
	v_cvt_pk_bf16_f32 v11, v6, v7
	ds_write_b128 v155, v[8:11]
	s_waitcnt lgkmcnt(0)
	s_barrier
; __device__ __forceinline__ void wmma_16x128(f32x4 (&acc)[8], const unsigned char* As, const unsigned char* Bs, int w, int lane) {
;     const int r = lane & 15, kg = lane >> 4;
; #pragma unroll
;     for (int ks = 0; ks < 4; ++ks) {
;         const bf16x8 a = *(const bf16x8*)(As + (16 * w + r) * RLD + (ks * 32 + kg * 8) * 2);
; #pragma unroll
;         for (int nt = 0; nt < 8; ++nt) { const bf16x8 b = *(const bf16x8*)(Bs + (16 * nt + r) * RLD + (ks * 32 + kg * 8) * 2);
;             acc[nt] = __builtin_amdgcn_mfma_f32_16x16x32_bf16(a, b, acc[nt], 0, 0, 0); }
;     }
; __device__ void ret_output(const Params& p, unsigned char* shm, int wg, int nwg) {
;     ...
;         f32x4 acc[8], oacc[8];
; #pragma unroll
;         for (int nt = 0; nt < 8; ++nt) acc[nt] = (f32x4){0.f, 0.f, 0.f, 0.f};
;         wmma_16x128(acc, Qs, Ks, w, lane);
;         __syncthreads();
	v_sub_f32_e32 v51, v2, v3
	ds_read_b128 v[2:5], v125
	ds_read_b128 v[6:9], v179 offset:34816
	ds_read_b128 v[10:13], v179 offset:39168
	ds_read_b128 v[14:17], v179 offset:43520
	ds_read_b128 v[18:21], v180 offset:34816
	ds_read_b128 v[30:33], v179 offset:60928
	ds_read_b128 v[22:25], v179 offset:52224
	ds_read_b128 v[26:29], v179 offset:56576
	ds_read_b128 v[34:37], v181 offset:34816
	s_waitcnt lgkmcnt(7)
	v_mfma_f32_16x16x32_bf16 v[6:9], v[2:5], v[6:9], 0
	s_waitcnt lgkmcnt(6)
	v_mfma_f32_16x16x32_bf16 v[10:13], v[2:5], v[10:13], 0
	s_waitcnt lgkmcnt(5)
	v_mfma_f32_16x16x32_bf16 v[14:17], v[2:5], v[14:17], 0
	s_waitcnt lgkmcnt(4)
	v_mfma_f32_16x16x32_bf16 v[18:21], v[2:5], v[18:21], 0
	s_waitcnt lgkmcnt(2)
	v_mfma_f32_16x16x32_bf16 v[22:25], v[2:5], v[22:25], 0
	s_waitcnt lgkmcnt(1)
	v_mfma_f32_16x16x32_bf16 v[26:29], v[2:5], v[26:29], 0
	v_mfma_f32_16x16x32_bf16 v[30:33], v[2:5], v[30:33], 0
	s_waitcnt lgkmcnt(0)
	v_mfma_f32_16x16x32_bf16 v[2:5], v[2:5], v[34:37], 0
	ds_read_b128 v[34:37], v125 offset:64
	ds_read_b128 v[156:159], v179 offset:34880
	s_waitcnt lgkmcnt(0)
	v_mfma_f32_16x16x32_bf16 v[6:9], v[34:37], v[156:159], v[6:9]
	ds_read_b128 v[156:159], v179 offset:39232
	s_waitcnt lgkmcnt(0)
	v_mfma_f32_16x16x32_bf16 v[10:13], v[34:37], v[156:159], v[10:13]
	ds_read_b128 v[156:159], v179 offset:43584
	s_waitcnt lgkmcnt(0)
	v_mfma_f32_16x16x32_bf16 v[14:17], v[34:37], v[156:159], v[14:17]
	ds_read_b128 v[156:159], v180 offset:34880
	s_waitcnt lgkmcnt(0)
	v_mfma_f32_16x16x32_bf16 v[18:21], v[34:37], v[156:159], v[18:21]
	ds_read_b128 v[156:159], v179 offset:52288
	s_waitcnt lgkmcnt(0)
	v_mfma_f32_16x16x32_bf16 v[22:25], v[34:37], v[156:159], v[22:25]
	ds_read_b128 v[156:159], v179 offset:56640
	s_waitcnt lgkmcnt(0)
	v_mfma_f32_16x16x32_bf16 v[26:29], v[34:37], v[156:159], v[26:29]
	ds_read_b128 v[156:159], v179 offset:60992
	s_waitcnt lgkmcnt(0)
	v_mfma_f32_16x16x32_bf16 v[30:33], v[34:37], v[156:159], v[30:33]
	ds_read_b128 v[156:159], v181 offset:34880
	s_waitcnt lgkmcnt(0)
	v_mfma_f32_16x16x32_bf16 v[2:5], v[34:37], v[156:159], v[2:5]
	ds_read_b128 v[34:37], v125 offset:128
	ds_read_b128 v[156:159], v179 offset:34944
	s_waitcnt lgkmcnt(0)
	v_mfma_f32_16x16x32_bf16 v[6:9], v[34:37], v[156:159], v[6:9]
	ds_read_b128 v[156:159], v179 offset:39296
	s_waitcnt lgkmcnt(0)
	v_mfma_f32_16x16x32_bf16 v[10:13], v[34:37], v[156:159], v[10:13]
	ds_read_b128 v[156:159], v179 offset:43648
	s_waitcnt lgkmcnt(0)
	v_mfma_f32_16x16x32_bf16 v[14:17], v[34:37], v[156:159], v[14:17]
	ds_read_b128 v[156:159], v180 offset:34944
	s_waitcnt lgkmcnt(0)
	v_mfma_f32_16x16x32_bf16 v[18:21], v[34:37], v[156:159], v[18:21]
	ds_read_b128 v[156:159], v179 offset:52352
	s_waitcnt lgkmcnt(0)
	v_mfma_f32_16x16x32_bf16 v[22:25], v[34:37], v[156:159], v[22:25]
	ds_read_b128 v[156:159], v179 offset:56704
	s_waitcnt lgkmcnt(0)
	v_mfma_f32_16x16x32_bf16 v[26:29], v[34:37], v[156:159], v[26:29]
	ds_read_b128 v[156:159], v179 offset:61056
	s_waitcnt lgkmcnt(0)
	v_mfma_f32_16x16x32_bf16 v[30:33], v[34:37], v[156:159], v[30:33]
	ds_read_b128 v[156:159], v181 offset:34944
	s_waitcnt lgkmcnt(0)
	v_mfma_f32_16x16x32_bf16 v[2:5], v[34:37], v[156:159], v[2:5]
	ds_read_b128 v[34:37], v125 offset:192
	ds_read_b128 v[156:159], v179 offset:35008
	s_waitcnt lgkmcnt(0)
	v_mfma_f32_16x16x32_bf16 v[6:9], v[34:37], v[156:159], v[6:9]
	ds_read_b128 v[156:159], v179 offset:39360
	s_waitcnt lgkmcnt(0)
	v_mfma_f32_16x16x32_bf16 v[10:13], v[34:37], v[156:159], v[10:13]
	ds_read_b128 v[156:159], v179 offset:43712
	s_waitcnt lgkmcnt(0)
	v_mfma_f32_16x16x32_bf16 v[14:17], v[34:37], v[156:159], v[14:17]
	ds_read_b128 v[156:159], v180 offset:35008
	v_add_u32_e32 v180, v64, v58
	s_waitcnt lgkmcnt(0)
	v_mfma_f32_16x16x32_bf16 v[18:21], v[34:37], v[156:159], v[18:21]
	ds_read_b128 v[156:159], v179 offset:52416
	s_waitcnt lgkmcnt(0)
	v_mfma_f32_16x16x32_bf16 v[22:25], v[34:37], v[156:159], v[22:25]
	ds_read_b128 v[156:159], v179 offset:56768
	s_waitcnt lgkmcnt(0)
	v_mfma_f32_16x16x32_bf16 v[26:29], v[34:37], v[156:159], v[26:29]
	ds_read_b128 v[156:159], v179 offset:61120
	v_add_u32_e32 v179, v67, v60
	s_waitcnt lgkmcnt(0)
	v_mfma_f32_16x16x32_bf16 v[30:33], v[34:37], v[156:159], v[30:33]
	ds_read_b128 v[156:159], v181 offset:35008
	s_waitcnt lgkmcnt(0)
	s_barrier
; __device__ __forceinline__ bf16_t f2bf(float f) { return (bf16_t)(cvt_pk_bf16(f, 0.f) & 0xffffu); }
; __device__ void ret_output(const Params& p, unsigned char* shm, int wg, int nwg) {
;     ...
; #pragma unroll
;         for (int nt = 0; nt < 8; ++nt)
; #pragma unroll
;             for (int j = 0; j < 4; ++j) { const int n = 16 * w + 4 * (lane >> 4) + j, m = 16 * nt + (lane & 15); const int dd = n > m ? n - m : m - n;
;                 *(bf16_t*)(Ks + n * RLD + m * 2) = f2bf(acc[nt][j] * __expf((float)dd * lg)); }
; #pragma unroll
;         for (int nt = 0; nt < 8; ++nt) acc[nt] = (f32x4){0.f, 0.f, 0.f, 0.f};
;         wmma_16x128(acc, Qs, Rs, w, lane);
	v_mfma_f32_16x16x32_bf16 v[2:5], v[34:37], v[156:159], v[2:5]
	v_mul_f32_e32 v34, v51, v80
	v_mul_f32_e32 v34, 0x3fb8aa3b, v34
	v_exp_f32_e32 v34, v34
	v_add_u32_e32 v156, v64, v56
	v_add_u32_e32 v157, v65, v60
	v_mul_f32_e32 v6, v34, v6
	v_cvt_pk_bf16_f32 v6, v6, v1
	ds_write_b16 v126, v6 offset:34816
	v_mul_f32_e32 v6, v51, v81
	v_mul_f32_e32 v6, 0x3fb8aa3b, v6
	v_exp_f32_e32 v6, v6
	v_add_u32_e32 v158, v66, v60
	v_add_u32_e32 v159, v65, v61
	v_add_u32_e32 v181, v66, v61
	v_mul_f32_e32 v6, v6, v7
	v_cvt_pk_bf16_f32 v6, v6, v1
	ds_write_b16 v126, v6 offset:35088
	v_mul_f32_e32 v6, v51, v82
	v_mul_f32_e32 v6, 0x3fb8aa3b, v6
	v_exp_f32_e32 v6, v6
	s_nop 0
	v_mul_f32_e32 v6, v6, v8
	v_cvt_pk_bf16_f32 v6, v6, v1
	ds_write_b16 v126, v6 offset:35360
	v_mul_f32_e32 v6, v51, v83
	v_mul_f32_e32 v6, 0x3fb8aa3b, v6
	v_exp_f32_e32 v6, v6
	s_nop 0
	v_mul_f32_e32 v6, v6, v9
	v_cvt_pk_bf16_f32 v6, v6, v1
	ds_write_b16 v126, v6 offset:35632
	v_mul_f32_e32 v6, v51, v84
	v_mul_f32_e32 v6, 0x3fb8aa3b, v6
	v_exp_f32_e32 v6, v6
	s_nop 0
	v_mul_f32_e32 v6, v6, v10
	v_cvt_pk_bf16_f32 v6, v6, v1
	ds_write_b16 v127, v6 offset:34816
	v_mul_f32_e32 v6, v51, v85
	v_mul_f32_e32 v6, 0x3fb8aa3b, v6
	v_exp_f32_e32 v6, v6
	s_nop 0
	v_mul_f32_e32 v6, v6, v11
	v_cvt_pk_bf16_f32 v6, v6, v1
	ds_write_b16 v127, v6 offset:35088
	v_mul_f32_e32 v6, v51, v86
	v_mul_f32_e32 v6, 0x3fb8aa3b, v6
	v_exp_f32_e32 v6, v6
	s_nop 0
	v_mul_f32_e32 v6, v6, v12
	v_cvt_pk_bf16_f32 v6, v6, v1
	ds_write_b16 v127, v6 offset:35360
	v_mul_f32_e32 v6, v51, v87
	v_mul_f32_e32 v6, 0x3fb8aa3b, v6
	v_exp_f32_e32 v6, v6
	s_nop 0
	v_mul_f32_e32 v6, v6, v13
	v_cvt_pk_bf16_f32 v6, v6, v1
	ds_write_b16 v127, v6 offset:35632
	v_mul_f32_e32 v6, v51, v88
	v_mul_f32_e32 v6, 0x3fb8aa3b, v6
	v_exp_f32_e32 v6, v6
	s_nop 0
	v_mul_f32_e32 v6, v6, v14
	v_cvt_pk_bf16_f32 v6, v6, v1
	ds_write_b16 v128, v6 offset:34816
	v_mul_f32_e32 v6, v51, v89
	v_mul_f32_e32 v6, 0x3fb8aa3b, v6
	v_exp_f32_e32 v6, v6
	s_nop 0
	v_mul_f32_e32 v6, v6, v15
	v_cvt_pk_bf16_f32 v6, v6, v1
	ds_write_b16 v128, v6 offset:35088
	v_mul_f32_e32 v6, v51, v90
	v_mul_f32_e32 v6, 0x3fb8aa3b, v6
	v_exp_f32_e32 v6, v6
	s_nop 0
	v_mul_f32_e32 v6, v6, v16
	v_cvt_pk_bf16_f32 v6, v6, v1
	ds_write_b16 v128, v6 offset:35360
	v_mul_f32_e32 v6, v51, v91
	v_mul_f32_e32 v6, 0x3fb8aa3b, v6
	v_exp_f32_e32 v6, v6
	s_nop 0
	v_mul_f32_e32 v6, v6, v17
	v_cvt_pk_bf16_f32 v6, v6, v1
	ds_write_b16 v128, v6 offset:35632
	v_mul_f32_e32 v6, v51, v92
	v_mul_f32_e32 v6, 0x3fb8aa3b, v6
	v_exp_f32_e32 v6, v6
	s_nop 0
	v_mul_f32_e32 v6, v6, v18
	v_cvt_pk_bf16_f32 v6, v6, v1
	ds_write_b16 v129, v6 offset:34816
	v_mul_f32_e32 v6, v51, v93
	v_mul_f32_e32 v6, 0x3fb8aa3b, v6
	v_exp_f32_e32 v6, v6
	s_nop 0
	v_mul_f32_e32 v6, v6, v19
	v_cvt_pk_bf16_f32 v6, v6, v1
	ds_write_b16 v129, v6 offset:35088
	v_mul_f32_e32 v6, v51, v94
	v_mul_f32_e32 v6, 0x3fb8aa3b, v6
	v_exp_f32_e32 v6, v6
	s_nop 0
	v_mul_f32_e32 v6, v6, v20
	v_cvt_pk_bf16_f32 v6, v6, v1
	ds_write_b16 v129, v6 offset:35360
	v_mul_f32_e32 v6, v51, v95
	v_mul_f32_e32 v6, 0x3fb8aa3b, v6
	v_exp_f32_e32 v6, v6
	s_nop 0
	v_mul_f32_e32 v6, v6, v21
	v_cvt_pk_bf16_f32 v6, v6, v1
	ds_write_b16 v129, v6 offset:35632
	v_mul_f32_e32 v6, v51, v96
	v_mul_f32_e32 v6, 0x3fb8aa3b, v6
	v_exp_f32_e32 v6, v6
	s_nop 0
	v_mul_f32_e32 v6, v6, v22
	v_cvt_pk_bf16_f32 v6, v6, v1
	ds_write_b16 v142, v6 offset:34816
	v_mul_f32_e32 v6, v51, v97
	v_mul_f32_e32 v6, 0x3fb8aa3b, v6
	v_exp_f32_e32 v6, v6
	s_nop 0
	v_mul_f32_e32 v6, v6, v23
	v_cvt_pk_bf16_f32 v6, v6, v1
	ds_write_b16 v142, v6 offset:35088
	v_mul_f32_e32 v6, v51, v98
	v_mul_f32_e32 v6, 0x3fb8aa3b, v6
	v_exp_f32_e32 v6, v6
	s_nop 0
	v_mul_f32_e32 v6, v6, v24
	v_cvt_pk_bf16_f32 v6, v6, v1
	ds_write_b16 v142, v6 offset:35360
	v_mul_f32_e32 v6, v51, v99
	v_mul_f32_e32 v6, 0x3fb8aa3b, v6
	v_exp_f32_e32 v6, v6
	s_nop 0
	v_mul_f32_e32 v6, v6, v25
	v_cvt_pk_bf16_f32 v6, v6, v1
	ds_write_b16 v142, v6 offset:35632
	v_mul_f32_e32 v6, v51, v100
	v_mul_f32_e32 v6, 0x3fb8aa3b, v6
	v_exp_f32_e32 v6, v6
	s_nop 0
	v_mul_f32_e32 v6, v6, v26
	v_cvt_pk_bf16_f32 v6, v6, v1
	ds_write_b16 v143, v6 offset:34816
	v_mul_f32_e32 v6, v51, v101
	v_mul_f32_e32 v6, 0x3fb8aa3b, v6
	v_exp_f32_e32 v6, v6
	s_nop 0
	v_mul_f32_e32 v6, v6, v27
	v_cvt_pk_bf16_f32 v6, v6, v1
	ds_write_b16 v143, v6 offset:35088
	v_mul_f32_e32 v6, v51, v102
	v_mul_f32_e32 v6, 0x3fb8aa3b, v6
	v_exp_f32_e32 v6, v6
	s_nop 0
	v_mul_f32_e32 v6, v6, v28
	v_cvt_pk_bf16_f32 v6, v6, v1
	ds_write_b16 v143, v6 offset:35360
	v_mul_f32_e32 v6, v51, v103
	v_mul_f32_e32 v6, 0x3fb8aa3b, v6
	v_exp_f32_e32 v6, v6
	s_nop 0
	v_mul_f32_e32 v6, v6, v29
	v_cvt_pk_bf16_f32 v6, v6, v1
	ds_write_b16 v143, v6 offset:35632
	v_mul_f32_e32 v6, v51, v104
	v_mul_f32_e32 v6, 0x3fb8aa3b, v6
	v_exp_f32_e32 v6, v6
	s_nop 0
	v_mul_f32_e32 v6, v6, v30
	v_cvt_pk_bf16_f32 v6, v6, v1
	ds_write_b16 v144, v6 offset:34816
	v_mul_f32_e32 v6, v51, v105
	v_mul_f32_e32 v6, 0x3fb8aa3b, v6
	v_exp_f32_e32 v6, v6
	s_nop 0
	v_mul_f32_e32 v6, v6, v31
	v_cvt_pk_bf16_f32 v6, v6, v1
	ds_write_b16 v144, v6 offset:35088
	v_mul_f32_e32 v6, v51, v106
	v_mul_f32_e32 v6, 0x3fb8aa3b, v6
	v_exp_f32_e32 v6, v6
	s_nop 0
	v_mul_f32_e32 v6, v6, v32
	v_cvt_pk_bf16_f32 v6, v6, v1
	ds_write_b16 v144, v6 offset:35360
	v_mul_f32_e32 v6, v51, v107
	v_mul_f32_e32 v6, 0x3fb8aa3b, v6
	v_exp_f32_e32 v6, v6
	s_nop 0
	v_mul_f32_e32 v6, v6, v33
	v_cvt_pk_bf16_f32 v6, v6, v1
	ds_write_b16 v144, v6 offset:35632
	v_mul_f32_e32 v6, v51, v108
	v_mul_f32_e32 v6, 0x3fb8aa3b, v6
	v_exp_f32_e32 v6, v6
	s_nop 0
	v_mul_f32_e32 v2, v6, v2
	v_cvt_pk_bf16_f32 v2, v2, v1
	ds_write_b16 v145, v2 offset:34816
	v_mul_f32_e32 v2, v51, v109
	v_mul_f32_e32 v2, 0x3fb8aa3b, v2
	v_exp_f32_e32 v2, v2
	s_nop 0
	v_mul_f32_e32 v2, v2, v3
	v_cvt_pk_bf16_f32 v2, v2, v1
	ds_write_b16 v145, v2 offset:35088
	v_mul_f32_e32 v2, v51, v110
	v_mul_f32_e32 v2, 0x3fb8aa3b, v2
	v_exp_f32_e32 v2, v2
	s_nop 0
	v_mul_f32_e32 v2, v2, v4
	v_cvt_pk_bf16_f32 v2, v2, v1
	ds_write_b16 v145, v2 offset:35360
	v_mul_f32_e32 v2, v51, v111
	v_mul_f32_e32 v2, 0x3fb8aa3b, v2
	v_exp_f32_e32 v2, v2
	s_nop 0
	v_mul_f32_e32 v2, v2, v5
	v_cvt_pk_bf16_f32 v2, v2, v1
	ds_write_b16 v145, v2 offset:35632
	ds_read_b128 v[2:5], v125
	ds_read_b128 v[6:9], v156
	ds_read_b128 v[10:13], v156 offset:4352
	ds_read_b128 v[14:17], v156 offset:8704
	ds_read_b128 v[18:21], v180
	ds_read_b128 v[30:33], v156 offset:26112
	ds_read_b128 v[22:25], v156 offset:17408
	ds_read_b128 v[26:29], v156 offset:21760
	ds_read_b128 v[34:37], v182
	s_waitcnt lgkmcnt(7)
; __device__ __forceinline__ unsigned cvt_pk_bf16(float lo, float hi) { unsigned r; asm("v_cvt_pk_bf16_f32 %0, %1, %2" : "=v"(r) : "v"(lo), "v"(hi)); return r; }
; __device__ void ret_output(const Params& p, unsigned char* shm, int wg, int nwg) {
;     ...
;         wmma_16x128(acc, Qs, Rs, w, lane);
; #pragma unroll
;         for (int nt = 0; nt < 8; ++nt)
; #pragma unroll
;             for (int j = 0; j < 4; ++j) { const int n = 16 * w + 4 * (lane >> 4) + j; oacc[nt][j] = acc[nt][j] * __expf((float)(n + 1) * lg); }
;         __syncthreads();
;         { const float* src = StB + (size_t)item * 16384;
; #pragma unroll
;           for (int it = 0; it < 4; ++it) { const int idx = it * NTHR + tid, v = idx >> 4, ch8 = idx & 15; const f32x4 a = *(const f32x4*)(src + v * 128 + ch8 * 8), bq = *(const f32x4*)(src + v * 128 + ch8 * 8 + 4);
;               u32x4 o; o.x = cvt_pk_bf16(a[0], a[1]); o.y = cvt_pk_bf16(a[2], a[3]); o.z = cvt_pk_bf16(bq[0], bq[1]); o.w = cvt_pk_bf16(bq[2], bq[3]); *(u32x4*)(Rs + v * RLD + ch8 * 16) = o; } }
	v_mfma_f32_16x16x32_bf16 v[6:9], v[2:5], v[6:9], 0
	ds_read_b128 v[184:187], v157
	s_waitcnt lgkmcnt(7)
	v_mfma_f32_16x16x32_bf16 v[10:13], v[2:5], v[10:13], 0
	s_waitcnt lgkmcnt(6)
	v_mfma_f32_16x16x32_bf16 v[14:17], v[2:5], v[14:17], 0
	s_waitcnt lgkmcnt(5)
	v_mfma_f32_16x16x32_bf16 v[18:21], v[2:5], v[18:21], 0
	s_waitcnt lgkmcnt(3)
	v_mfma_f32_16x16x32_bf16 v[22:25], v[2:5], v[22:25], 0
	s_waitcnt lgkmcnt(2)
	v_mfma_f32_16x16x32_bf16 v[26:29], v[2:5], v[26:29], 0
	v_mfma_f32_16x16x32_bf16 v[30:33], v[2:5], v[30:33], 0
	s_waitcnt lgkmcnt(1)
	v_mfma_f32_16x16x32_bf16 v[2:5], v[2:5], v[34:37], 0
	ds_read_b128 v[34:37], v125 offset:64
	s_waitcnt lgkmcnt(0)
	v_mfma_f32_16x16x32_bf16 v[184:187], v[34:37], v[184:187], v[6:9]
	s_nop 2
	ds_read_b128 v[6:9], v146 offset:4352
	s_waitcnt lgkmcnt(0)
	v_mfma_f32_16x16x32_bf16 v[188:191], v[34:37], v[6:9], v[10:13]
	ds_read_b128 v[6:9], v146 offset:8704
	s_nop 1
	ds_read_b128 v[10:13], v159
	s_waitcnt lgkmcnt(1)
	v_mfma_f32_16x16x32_bf16 v[198:201], v[34:37], v[6:9], v[14:17]
	ds_read_b128 v[6:9], v158
	s_nop 1
	ds_read_b128 v[14:17], v147 offset:4352
	s_waitcnt lgkmcnt(1)
	v_mfma_f32_16x16x32_bf16 v[202:205], v[34:37], v[6:9], v[18:21]
	ds_read_b128 v[6:9], v146 offset:17408
	s_nop 1
	ds_read_b128 v[18:21], v147 offset:8704
	s_waitcnt lgkmcnt(1)
	v_mfma_f32_16x16x32_bf16 v[206:209], v[34:37], v[6:9], v[22:25]
	ds_read_b128 v[6:9], v146 offset:21760
	s_nop 1
	ds_read_b128 v[22:25], v181
	s_waitcnt lgkmcnt(1)
	v_mfma_f32_16x16x32_bf16 v[210:213], v[34:37], v[6:9], v[26:29]
	ds_read_b128 v[6:9], v146 offset:26112
	s_nop 1
	ds_read_b128 v[26:29], v147 offset:17408
	s_waitcnt lgkmcnt(1)
	v_mfma_f32_16x16x32_bf16 v[214:217], v[34:37], v[6:9], v[30:33]
	ds_read_b128 v[6:9], v179
	s_nop 1
	ds_read_b128 v[30:33], v147 offset:21760
	s_waitcnt lgkmcnt(1)
	v_mfma_f32_16x16x32_bf16 v[2:5], v[34:37], v[6:9], v[2:5]
	ds_read_b128 v[6:9], v125 offset:128
	ds_read_b128 v[34:37], v147 offset:26112
	s_waitcnt lgkmcnt(1)
	v_mfma_f32_16x16x32_bf16 v[10:13], v[6:9], v[10:13], v[184:187]
	s_nop 2
	ds_read_b128 v[184:187], v183
	v_mfma_f32_16x16x32_bf16 v[14:17], v[6:9], v[14:17], v[188:191]
	v_mfma_f32_16x16x32_bf16 v[18:21], v[6:9], v[18:21], v[198:201]
	v_mfma_f32_16x16x32_bf16 v[22:25], v[6:9], v[22:25], v[202:205]
	v_mfma_f32_16x16x32_bf16 v[26:29], v[6:9], v[26:29], v[206:209]
	v_mfma_f32_16x16x32_bf16 v[30:33], v[6:9], v[30:33], v[210:213]
	s_waitcnt lgkmcnt(1)
	v_mfma_f32_16x16x32_bf16 v[34:37], v[6:9], v[34:37], v[214:217]
	s_waitcnt lgkmcnt(0)
	v_mfma_f32_16x16x32_bf16 v[2:5], v[6:9], v[184:187], v[2:5]
	ds_read_b128 v[6:9], v125 offset:192
	v_add_u32_e32 v184, v65, v62
	ds_read_b128 v[186:189], v184
	s_waitcnt lgkmcnt(0)
	v_mfma_f32_16x16x32_bf16 v[10:13], v[6:9], v[186:189], v[10:13]
	ds_read_b128 v[186:189], v148 offset:4352
	v_add_u32_e32 v185, v66, v62
	s_waitcnt lgkmcnt(0)
	v_mfma_f32_16x16x32_bf16 v[14:17], v[6:9], v[186:189], v[14:17]
	ds_read_b128 v[186:189], v148 offset:8704
	s_waitcnt lgkmcnt(0)
	v_mfma_f32_16x16x32_bf16 v[18:21], v[6:9], v[186:189], v[18:21]
	ds_read_b128 v[186:189], v185
	s_waitcnt lgkmcnt(0)
	v_mfma_f32_16x16x32_bf16 v[22:25], v[6:9], v[186:189], v[22:25]
	ds_read_b128 v[186:189], v148 offset:17408
	s_waitcnt lgkmcnt(0)
	v_mfma_f32_16x16x32_bf16 v[188:191], v[6:9], v[186:189], v[26:29]
	v_add_u32_e32 v186, v67, v62
	s_nop 1
	ds_read_b128 v[26:29], v148 offset:21760
	v_add_u32_e32 v187, v68, v56
	s_waitcnt lgkmcnt(0)
	v_mfma_f32_16x16x32_bf16 v[198:201], v[6:9], v[26:29], v[30:33]
	ds_read_b128 v[26:29], v148 offset:26112
	s_waitcnt lgkmcnt(0)
	v_mfma_f32_16x16x32_bf16 v[202:205], v[6:9], v[26:29], v[34:37]
	ds_read_b128 v[26:29], v186
	s_waitcnt lgkmcnt(0)
	s_barrier
	v_mfma_f32_16x16x32_bf16 v[2:5], v[6:9], v[26:29], v[2:5]
	v_mul_f32_e32 v6, v51, v112
	v_mul_f32_e32 v7, v51, v113
	v_mul_f32_e32 v6, 0x3fb8aa3b, v6
	v_mul_f32_e32 v7, 0x3fb8aa3b, v7
	v_mul_f32_e32 v8, v51, v114
	v_mul_f32_e32 v9, v51, v115
	v_exp_f32_e32 v6, v6
	v_exp_f32_e32 v7, v7
	v_mul_f32_e32 v8, 0x3fb8aa3b, v8
	v_mul_f32_e32 v9, 0x3fb8aa3b, v9
	v_exp_f32_e32 v8, v8
	v_exp_f32_e32 v9, v9
	v_pk_mul_f32 v[26:27], v[6:7], v[18:19]
	v_pk_mul_f32 v[18:19], v[6:7], v[188:189]
	v_lshl_add_u64 v[188:189], v[192:193], 0, v[42:43]
	v_pk_mul_f32 v[34:35], v[6:7], v[10:11]
	v_pk_mul_f32 v[36:37], v[8:9], v[12:13]
	v_pk_mul_f32 v[30:31], v[6:7], v[14:15]
	v_pk_mul_f32 v[32:33], v[8:9], v[16:17]
	v_pk_mul_f32 v[28:29], v[8:9], v[20:21]
	v_pk_mul_f32 v[22:23], v[6:7], v[22:23]
	v_pk_mul_f32 v[24:25], v[8:9], v[24:25]
	v_pk_mul_f32 v[20:21], v[8:9], v[190:191]
	v_pk_mul_f32 v[14:15], v[6:7], v[198:199]
	v_pk_mul_f32 v[16:17], v[8:9], v[200:201]
	v_pk_mul_f32 v[10:11], v[6:7], v[202:203]
	v_pk_mul_f32 v[12:13], v[8:9], v[204:205]
	v_pk_mul_f32 v[2:3], v[6:7], v[2:3]
	v_pk_mul_f32 v[4:5], v[8:9], v[4:5]
	global_load_dwordx4 v[6:9], v[188:189], off offset:16
	s_nop 0
	global_load_dwordx4 v[188:191], v[188:189], off
	s_waitcnt vmcnt(0)
	v_cvt_pk_bf16_f32 v188, v188, v189
	v_cvt_pk_bf16_f32 v189, v190, v191
	v_cvt_pk_bf16_f32 v190, v6, v7
	v_cvt_pk_bf16_f32 v191, v8, v9
	ds_write_b128 v152, v[188:191]
	v_lshl_add_u64 v[188:189], v[192:193], 0, v[44:45]
	global_load_dwordx4 v[6:9], v[188:189], off offset:16
	s_nop 0
	global_load_dwordx4 v[188:191], v[188:189], off
	s_waitcnt vmcnt(0)
	v_cvt_pk_bf16_f32 v188, v188, v189
	v_cvt_pk_bf16_f32 v189, v190, v191
	v_cvt_pk_bf16_f32 v190, v6, v7
	v_cvt_pk_bf16_f32 v191, v8, v9
	ds_write_b128 v153, v[188:191]
	v_lshl_add_u64 v[152:153], v[192:193], 0, v[46:47]
	global_load_dwordx4 v[6:9], v[152:153], off offset:16
	global_load_dwordx4 v[188:191], v[152:153], off
	s_waitcnt vmcnt(0)
; __device__ __forceinline__ unsigned cvt_pk_bf16(float lo, float hi) { unsigned r; asm("v_cvt_pk_bf16_f32 %0, %1, %2" : "=v"(r) : "v"(lo), "v"(hi)); return r; }
; __device__ void ret_output(const Params& p, unsigned char* shm, int wg, int nwg) {
;     ...
;         { const float* src = StB + (size_t)item * 16384;
; #pragma unroll
;           for (int it = 0; it < 4; ++it) { const int idx = it * NTHR + tid, v = idx >> 4, ch8 = idx & 15; const f32x4 a = *(const f32x4*)(src + v * 128 + ch8 * 8), bq = *(const f32x4*)(src + v * 128 + ch8 * 8 + 4);
;               u32x4 o; o.x = cvt_pk_bf16(a[0], a[1]); o.y = cvt_pk_bf16(a[2], a[3]); o.z = cvt_pk_bf16(bq[0], bq[1]); o.w = cvt_pk_bf16(bq[2], bq[3]); *(u32x4*)(Rs + v * RLD + ch8 * 16) = o; } }
;         wmma_16x128(oacc, Ks, Vt, w, lane);
;         __syncthreads();
	v_cvt_pk_bf16_f32 v188, v188, v189
	v_cvt_pk_bf16_f32 v189, v190, v191
	v_cvt_pk_bf16_f32 v190, v6, v7
	v_cvt_pk_bf16_f32 v191, v8, v9
	ds_write_b128 v154, v[188:191]
	v_lshl_add_u64 v[152:153], v[192:193], 0, v[48:49]
	global_load_dwordx4 v[6:9], v[152:153], off offset:16
	global_load_dwordx4 v[188:191], v[152:153], off
	s_waitcnt vmcnt(0)
	v_cvt_pk_bf16_f32 v188, v188, v189
	v_cvt_pk_bf16_f32 v189, v190, v191
	v_cvt_pk_bf16_f32 v190, v6, v7
	v_cvt_pk_bf16_f32 v191, v8, v9
	ds_write_b128 v155, v[188:191]
	ds_read_b128 v[6:9], v125 offset:34816
	ds_read_b128 v[152:155], v187
	s_waitcnt lgkmcnt(0)
	v_mfma_f32_16x16x32_bf16 v[34:37], v[6:9], v[152:155], v[34:37]
	ds_read_b128 v[152:155], v187 offset:4352
	s_waitcnt lgkmcnt(0)
	v_mfma_f32_16x16x32_bf16 v[30:33], v[6:9], v[152:155], v[30:33]
	ds_read_b128 v[152:155], v187 offset:8704
	s_waitcnt lgkmcnt(0)
	v_mfma_f32_16x16x32_bf16 v[26:29], v[6:9], v[152:155], v[26:29]
	v_add_u32_e32 v152, v68, v58
	ds_read_b128 v[152:155], v152
	s_waitcnt lgkmcnt(0)
	v_mfma_f32_16x16x32_bf16 v[22:25], v[6:9], v[152:155], v[22:25]
	ds_read_b128 v[152:155], v187 offset:17408
	s_waitcnt lgkmcnt(0)
	v_mfma_f32_16x16x32_bf16 v[18:21], v[6:9], v[152:155], v[18:21]
	ds_read_b128 v[152:155], v187 offset:21760
	s_waitcnt lgkmcnt(0)
	v_mfma_f32_16x16x32_bf16 v[14:17], v[6:9], v[152:155], v[14:17]
	ds_read_b128 v[152:155], v187 offset:26112
	s_waitcnt lgkmcnt(0)
	v_mfma_f32_16x16x32_bf16 v[10:13], v[6:9], v[152:155], v[10:13]
	v_add_u32_e32 v152, v68, v59
	ds_read_b128 v[152:155], v152
	s_waitcnt lgkmcnt(0)
	v_mfma_f32_16x16x32_bf16 v[2:5], v[6:9], v[152:155], v[2:5]
	ds_read_b128 v[6:9], v125 offset:34880
	v_add_u32_e32 v152, v69, v60
	ds_read_b128 v[152:155], v152
	s_waitcnt lgkmcnt(0)
	v_mfma_f32_16x16x32_bf16 v[34:37], v[6:9], v[152:155], v[34:37]
	ds_read_b128 v[152:155], v149 offset:4352
	s_waitcnt lgkmcnt(0)
	v_mfma_f32_16x16x32_bf16 v[30:33], v[6:9], v[152:155], v[30:33]
	ds_read_b128 v[152:155], v149 offset:8704
	s_waitcnt lgkmcnt(0)
	v_mfma_f32_16x16x32_bf16 v[26:29], v[6:9], v[152:155], v[26:29]
	v_add_u32_e32 v152, v70, v60
	ds_read_b128 v[152:155], v152
	s_waitcnt lgkmcnt(0)
	v_mfma_f32_16x16x32_bf16 v[22:25], v[6:9], v[152:155], v[22:25]
	ds_read_b128 v[152:155], v149 offset:17408
	s_waitcnt lgkmcnt(0)
	v_mfma_f32_16x16x32_bf16 v[18:21], v[6:9], v[152:155], v[18:21]
	ds_read_b128 v[152:155], v149 offset:21760
	s_waitcnt lgkmcnt(0)
	v_mfma_f32_16x16x32_bf16 v[14:17], v[6:9], v[152:155], v[14:17]
	ds_read_b128 v[152:155], v149 offset:26112
	s_waitcnt lgkmcnt(0)
	v_mfma_f32_16x16x32_bf16 v[10:13], v[6:9], v[152:155], v[10:13]
	v_add_u32_e32 v152, v71, v60
	ds_read_b128 v[152:155], v152
	s_waitcnt lgkmcnt(0)
	v_mfma_f32_16x16x32_bf16 v[2:5], v[6:9], v[152:155], v[2:5]
	ds_read_b128 v[6:9], v125 offset:34944
	v_add_u32_e32 v152, v69, v61
	ds_read_b128 v[152:155], v152
	s_waitcnt lgkmcnt(0)
	v_mfma_f32_16x16x32_bf16 v[152:155], v[6:9], v[152:155], v[34:37]
	s_nop 2
	ds_read_b128 v[34:37], v150 offset:4352
	s_waitcnt lgkmcnt(0)
	v_mfma_f32_16x16x32_bf16 v[188:191], v[6:9], v[34:37], v[30:33]
	ds_read_b128 v[34:37], v125 offset:35008
	s_nop 1
	ds_read_b128 v[30:33], v150 offset:8704
	s_waitcnt lgkmcnt(0)
	v_mfma_f32_16x16x32_bf16 v[26:29], v[6:9], v[30:33], v[26:29]
	v_add_u32_e32 v30, v70, v61
	ds_read_b128 v[30:33], v30
	s_waitcnt lgkmcnt(0)
	v_mfma_f32_16x16x32_bf16 v[22:25], v[6:9], v[30:33], v[22:25]
	ds_read_b128 v[30:33], v150 offset:17408
	s_waitcnt lgkmcnt(0)
	v_mfma_f32_16x16x32_bf16 v[18:21], v[6:9], v[30:33], v[18:21]
	ds_read_b128 v[30:33], v150 offset:21760
	s_waitcnt lgkmcnt(0)
	v_mfma_f32_16x16x32_bf16 v[198:201], v[6:9], v[30:33], v[14:17]
	s_nop 2
	ds_read_b128 v[14:17], v150 offset:26112
	s_waitcnt lgkmcnt(0)
	v_mfma_f32_16x16x32_bf16 v[10:13], v[6:9], v[14:17], v[10:13]
	v_add_u32_e32 v14, v71, v61
	ds_read_b128 v[14:17], v14
	s_waitcnt lgkmcnt(0)
	v_mfma_f32_16x16x32_bf16 v[30:33], v[6:9], v[14:17], v[2:5]
	ds_read_b128 v[14:17], v151 offset:8704
	s_nop 1
	v_add_u32_e32 v2, v69, v62
	ds_read_b128 v[2:5], v2
	s_waitcnt lgkmcnt(1)
	v_mfma_f32_16x16x32_bf16 v[14:17], v[34:37], v[14:17], v[26:29]
	s_nop 2
	v_add_u32_e32 v26, v70, v62
	ds_read_b128 v[26:29], v26
	s_waitcnt lgkmcnt(1)
	v_mfma_f32_16x16x32_bf16 v[6:9], v[34:37], v[2:5], v[152:155]
	ds_read_b128 v[2:5], v151 offset:4352
	s_waitcnt lgkmcnt(1)
	v_mfma_f32_16x16x32_bf16 v[26:29], v[34:37], v[26:29], v[22:25]
	ds_read_b128 v[152:155], v151 offset:26112
	s_nop 1
	ds_read_b128 v[22:25], v151 offset:17408
	s_waitcnt lgkmcnt(0)
	v_mfma_f32_16x16x32_bf16 v[18:21], v[34:37], v[22:25], v[18:21]
	ds_read_b128 v[22:25], v151 offset:21760
	v_mfma_f32_16x16x32_bf16 v[10:13], v[34:37], v[152:155], v[10:13]
	v_add_u32_e32 v152, v71, v62
	ds_read_b128 v[152:155], v152
	s_waitcnt lgkmcnt(0)
	v_mfma_f32_16x16x32_bf16 v[2:5], v[34:37], v[2:5], v[188:191]
	s_barrier
; __device__ void ret_output(const Params& p, unsigned char* shm, int wg, int nwg) {
;     ...
;         wmma_16x128(oacc, Ks, Vt, w, lane);
;         __syncthreads();
; #pragma unroll
;         for (int nt = 0; nt < 8; ++nt) acc[nt] = (f32x4){0.f, 0.f, 0.f, 0.f};
;         wmma_16x128(acc, Qs, Rs, w, lane);
	v_mfma_f32_16x16x32_bf16 v[22:25], v[34:37], v[22:25], v[198:201]
	v_mfma_f32_16x16x32_bf16 v[30:33], v[34:37], v[152:155], v[30:33]
	ds_read_b128 v[34:37], v125
	ds_read_b128 v[152:155], v156
	ds_read_b128 v[188:191], v156 offset:4352
	ds_read_b128 v[198:201], v156 offset:8704
	ds_read_b128 v[202:205], v180
	ds_read_b128 v[214:217], v156 offset:26112
	ds_read_b128 v[206:209], v156 offset:17408
	ds_read_b128 v[210:213], v156 offset:21760
	ds_read_b128 v[218:221], v182
	s_waitcnt lgkmcnt(7)
	v_mfma_f32_16x16x32_bf16 v[152:155], v[34:37], v[152:155], 0
	s_waitcnt lgkmcnt(6)
	v_mfma_f32_16x16x32_bf16 v[188:191], v[34:37], v[188:191], 0
	s_waitcnt lgkmcnt(5)
	v_mfma_f32_16x16x32_bf16 v[198:201], v[34:37], v[198:201], 0
	s_waitcnt lgkmcnt(4)
	v_mfma_f32_16x16x32_bf16 v[202:205], v[34:37], v[202:205], 0
	s_waitcnt lgkmcnt(2)
	v_mfma_f32_16x16x32_bf16 v[206:209], v[34:37], v[206:209], 0
	s_waitcnt lgkmcnt(1)
	v_mfma_f32_16x16x32_bf16 v[210:213], v[34:37], v[210:213], 0
	v_mfma_f32_16x16x32_bf16 v[214:217], v[34:37], v[214:217], 0
	s_waitcnt lgkmcnt(0)
	v_mfma_f32_16x16x32_bf16 v[34:37], v[34:37], v[218:221], 0
	ds_read_b128 v[218:221], v125 offset:64
	ds_read_b128 v[222:225], v157
	s_waitcnt lgkmcnt(0)
	v_mfma_f32_16x16x32_bf16 v[152:155], v[218:221], v[222:225], v[152:155]
	ds_read_b128 v[222:225], v146 offset:4352
	s_waitcnt lgkmcnt(0)
	v_mfma_f32_16x16x32_bf16 v[188:191], v[218:221], v[222:225], v[188:191]
	ds_read_b128 v[222:225], v146 offset:8704
	s_waitcnt lgkmcnt(0)
	v_mfma_f32_16x16x32_bf16 v[198:201], v[218:221], v[222:225], v[198:201]
	ds_read_b128 v[222:225], v158
	s_waitcnt lgkmcnt(0)
	v_mfma_f32_16x16x32_bf16 v[202:205], v[218:221], v[222:225], v[202:205]
	ds_read_b128 v[222:225], v146 offset:17408
	s_waitcnt lgkmcnt(0)
	v_mfma_f32_16x16x32_bf16 v[206:209], v[218:221], v[222:225], v[206:209]
	ds_read_b128 v[222:225], v146 offset:21760
	s_waitcnt lgkmcnt(0)
	v_mfma_f32_16x16x32_bf16 v[210:213], v[218:221], v[222:225], v[210:213]
	ds_read_b128 v[222:225], v146 offset:26112
	s_waitcnt lgkmcnt(0)
	v_mfma_f32_16x16x32_bf16 v[214:217], v[218:221], v[222:225], v[214:217]
	ds_read_b128 v[222:225], v179
	s_waitcnt lgkmcnt(0)
	v_mfma_f32_16x16x32_bf16 v[34:37], v[218:221], v[222:225], v[34:37]
	ds_read_b128 v[218:221], v125 offset:128
	ds_read_b128 v[156:159], v159
	s_waitcnt lgkmcnt(0)
	v_mfma_f32_16x16x32_bf16 v[152:155], v[218:221], v[156:159], v[152:155]
	ds_read_b128 v[156:159], v147 offset:4352
	s_waitcnt lgkmcnt(0)
	v_mfma_f32_16x16x32_bf16 v[156:159], v[218:221], v[156:159], v[188:191]
	s_nop 2
	ds_read_b128 v[188:191], v147 offset:8704
	s_waitcnt lgkmcnt(0)
	v_mfma_f32_16x16x32_bf16 v[188:191], v[218:221], v[188:191], v[198:201]
	s_nop 2
	ds_read_b128 v[198:201], v181
	ds_read_b128 v[180:183], v183
	s_waitcnt lgkmcnt(1)
	v_mfma_f32_16x16x32_bf16 v[198:201], v[218:221], v[198:201], v[202:205]
	s_nop 2
	ds_read_b128 v[202:205], v147 offset:17408
	s_waitcnt lgkmcnt(0)
	v_mfma_f32_16x16x32_bf16 v[202:205], v[218:221], v[202:205], v[206:209]
	s_nop 2
	ds_read_b128 v[206:209], v147 offset:21760
	s_waitcnt lgkmcnt(0)
	v_mfma_f32_16x16x32_bf16 v[206:209], v[218:221], v[206:209], v[210:213]
	s_nop 2
	ds_read_b128 v[210:213], v147 offset:26112
	s_waitcnt lgkmcnt(0)
	v_mfma_f32_16x16x32_bf16 v[210:213], v[218:221], v[210:213], v[214:217]
	v_mfma_f32_16x16x32_bf16 v[34:37], v[218:221], v[180:183], v[34:37]
	ds_read_b128 v[180:183], v125 offset:192
	s_nop 0
	ds_read_b128 v[214:217], v184
	ds_read_b128 v[218:221], v148 offset:8704
	s_waitcnt lgkmcnt(1)
	v_mfma_f32_16x16x32_bf16 v[214:217], v[180:183], v[214:217], v[152:155]
	s_nop 2
	ds_read_b128 v[152:155], v148 offset:4352
	s_waitcnt lgkmcnt(1)
	v_mfma_f32_16x16x32_bf16 v[188:191], v[180:183], v[218:221], v[188:191]
	ds_read_b128 v[218:221], v185
	ds_read_b128 v[184:187], v186
	s_waitcnt lgkmcnt(1)
	v_mfma_f32_16x16x32_bf16 v[198:201], v[180:183], v[218:221], v[198:201]
	ds_read_b128 v[218:221], v148 offset:17408
	s_waitcnt lgkmcnt(0)
	v_mfma_f32_16x16x32_bf16 v[202:205], v[180:183], v[218:221], v[202:205]
	ds_read_b128 v[218:221], v148 offset:21760
	s_waitcnt lgkmcnt(0)
	v_mfma_f32_16x16x32_bf16 v[206:209], v[180:183], v[218:221], v[206:209]
	ds_read_b128 v[218:221], v148 offset:26112
	v_mfma_f32_16x16x32_bf16 v[154:157], v[180:183], v[152:155], v[156:159]
	s_waitcnt lgkmcnt(0)
; __device__ __forceinline__ float bf2f(bf16_t b) { return __uint_as_float(((unsigned)b) << 16); }
; __device__ __forceinline__ bf16_t f2bf(float f) { return (bf16_t)(cvt_pk_bf16(f, 0.f) & 0xffffu); }
; __device__ __forceinline__ float allreduce16(float x) { x += dppf(x, 0); x += dppf(x, 1); x += dppf(x, 2); x += dppf(x, 3); return x; }
; __device__ __forceinline__ float sigmoidf_(float x) { return __builtin_amdgcn_rcpf(1.0f + __expf(-x)); }
; __device__ void ret_output(const Params& p, unsigned char* shm, int wg, int nwg) {
;     ...
;         float ss[4] = {0.f, 0.f, 0.f, 0.f};
; #pragma unroll
;         for (int nt = 0; nt < 8; ++nt)
; #pragma unroll
;             for (int j = 0; j < 4; ++j) { const int n = 16 * w + 4 * (lane >> 4) + j; oacc[nt][j] += acc[nt][j] * __expf((float)(128 - n) * lg); ss[j] += oacc[nt][j] * oacc[nt][j]; }
; #pragma unroll
;         for (int j = 0; j < 4; ++j) {
;             const float rs = rsqrtf(allreduce16(ss[j]) * (1.0f / 128.0f) + 1e-6f);
;             const int n = 16 * w + 4 * (lane >> 4) + j;
;             bf16_t* gp = Z + (size_t)(b * T + c * 128 + n) * ZLD + ZC_RET + 2304 + h * 128 + (lane & 15);
; #pragma unroll
;             for (int nt = 0; nt < 8; ++nt) { const float gv = bf2f(gp[16 * nt]); gp[16 * nt] = (ABL == 3) ? (bf16_t)0 : f2bf(oacc[nt][j] * rs * gv * sigmoidf_(gv)); }
	v_mfma_f32_16x16x32_bf16 v[210:213], v[180:183], v[218:221], v[210:213]
	v_mfma_f32_16x16x32_bf16 v[180:183], v[180:183], v[184:187], v[34:37]
	s_nop 2
	v_mul_f32_e32 v34, v51, v116
	v_mul_f32_e32 v34, 0x3fb8aa3b, v34
	v_exp_f32_e32 v158, v34
	s_nop 0
	v_fma_f32 v153, v158, v214, v6
	v_mul_f32_e32 v6, v51, v117
	v_mul_f32_e32 v6, 0x3fb8aa3b, v6
	v_exp_f32_e32 v184, v6
	v_mul_f32_e32 v6, v51, v118
	v_mul_f32_e32 v6, 0x3fb8aa3b, v6
	v_exp_f32_e32 v186, v6
	v_mul_f32_e32 v6, v51, v119
	v_mul_f32_e32 v6, 0x3fb8aa3b, v6
	v_fma_f32 v37, v184, v215, v7
	v_exp_f32_e32 v192, v6
	v_fma_f32 v154, v158, v154, v2
	v_fma_f32 v152, v184, v155, v3
	v_mov_b32_e32 v2, v188
	v_mov_b32_e32 v3, v198
	v_mov_b32_e32 v6, v14
	v_mov_b32_e32 v7, v26
	v_mul_f32_e32 v51, v154, v154
	v_pk_fma_f32 v[34:35], v[158:159], v[2:3], v[6:7] op_sel_hi:[0,1,1]
	v_fmac_f32_e32 v51, v153, v153
	v_pk_mul_f32 v[2:3], v[34:35], v[34:35]
	v_mov_b32_e32 v198, v189
	v_mov_b32_e32 v26, v15
	v_mul_f32_e32 v155, v152, v152
	v_add_f32_e32 v2, v51, v2
	v_pk_fma_f32 v[26:27], v[184:185], v[198:199], v[26:27] op_sel_hi:[0,1,1]
	v_fmac_f32_e32 v155, v37, v37
	v_add_f32_e32 v51, v2, v3
	v_pk_mul_f32 v[2:3], v[26:27], v[26:27]
	v_fma_f32 v36, v186, v156, v4
	v_add_f32_e32 v2, v155, v2
	v_add_f32_e32 v155, v2, v3
	v_mov_b32_e32 v2, v190
	v_mov_b32_e32 v3, v200
	v_mov_b32_e32 v6, v16
	v_mov_b32_e32 v7, v28
	v_fma_f32 v8, v186, v216, v8
	v_mul_f32_e32 v4, v36, v36
	v_pk_fma_f32 v[14:15], v[186:187], v[2:3], v[6:7] op_sel_hi:[0,1,1]
	v_fmac_f32_e32 v4, v8, v8
	v_pk_mul_f32 v[2:3], v[14:15], v[14:15]
	v_fmac_f32_e32 v5, v192, v157
	v_add_f32_e32 v2, v4, v2
	v_mov_b32_e32 v200, v191
	v_mov_b32_e32 v28, v17
	v_fmac_f32_e32 v9, v192, v217
	v_mul_f32_e32 v156, v5, v5
	v_add_f32_e32 v4, v2, v3
	v_pk_fma_f32 v[2:3], v[192:193], v[200:201], v[28:29] op_sel_hi:[0,1,1]
	v_fmac_f32_e32 v156, v9, v9
	v_pk_mul_f32 v[6:7], v[2:3], v[2:3]
	v_mov_b32_e32 v16, v18
	v_add_f32_e32 v6, v156, v6
	v_add_f32_e32 v156, v6, v7
	v_mov_b32_e32 v6, v202
	v_mov_b32_e32 v7, v206
	v_mov_b32_e32 v17, v22
	v_pk_fma_f32 v[28:29], v[158:159], v[6:7], v[16:17] op_sel_hi:[0,1,1]
	v_pk_mul_f32 v[6:7], v[28:29], v[28:29]
	v_mov_b32_e32 v206, v203
	v_mov_b32_e32 v22, v19
	v_add_f32_e32 v6, v51, v6
	v_pk_fma_f32 v[22:23], v[184:185], v[206:207], v[22:23] op_sel_hi:[0,1,1]
	v_add_f32_e32 v51, v6, v7
	v_pk_mul_f32 v[6:7], v[22:23], v[22:23]
	v_mov_b32_e32 v16, v20
	v_add_f32_e32 v6, v155, v6
	v_add_f32_e32 v155, v6, v7
	v_mov_b32_e32 v6, v204
	v_mov_b32_e32 v7, v208
	v_mov_b32_e32 v17, v24
	v_pk_fma_f32 v[16:17], v[186:187], v[6:7], v[16:17] op_sel_hi:[0,1,1]
	v_pk_mul_f32 v[6:7], v[16:17], v[16:17]
	v_mov_b32_e32 v208, v205
	v_add_f32_e32 v4, v4, v6
	v_mov_b32_e32 v24, v21
	v_add_f32_e32 v4, v4, v7
	v_pk_fma_f32 v[6:7], v[192:193], v[208:209], v[24:25] op_sel_hi:[0,1,1]
	v_pk_mul_f32 v[18:19], v[6:7], v[6:7]
	v_mov_b32_e32 v20, v10
	v_add_f32_e32 v18, v156, v18
	v_add_f32_e32 v156, v18, v19
	v_mov_b32_e32 v18, v210
	v_mov_b32_e32 v19, v180
	v_mov_b32_e32 v21, v30
	v_pk_fma_f32 v[24:25], v[158:159], v[18:19], v[20:21] op_sel_hi:[0,1,1]
	v_pk_mul_f32 v[18:19], v[24:25], v[24:25]
	v_mov_b32_e32 v180, v211
	v_mov_b32_e32 v30, v11
	v_add_f32_e32 v10, v51, v18
	v_pk_fma_f32 v[20:21], v[184:185], v[180:181], v[30:31] op_sel_hi:[0,1,1]
	v_add_f32_e32 v51, v10, v19
	v_pk_mul_f32 v[10:11], v[20:21], v[20:21]
	v_mov_b32_e32 v18, v12
	v_add_f32_e32 v10, v155, v10
	v_add_f32_e32 v155, v10, v11
	v_mov_b32_e32 v10, v212
	v_mov_b32_e32 v11, v182
	v_mov_b32_e32 v19, v32
	v_pk_fma_f32 v[18:19], v[186:187], v[10:11], v[18:19] op_sel_hi:[0,1,1]
	v_pk_mul_f32 v[10:11], v[18:19], v[18:19]
	v_mov_b32_e32 v182, v213
	v_add_f32_e32 v4, v4, v10
	v_mov_b32_e32 v32, v13
	v_add_f32_e32 v31, v4, v11
	v_pk_fma_f32 v[10:11], v[192:193], v[182:183], v[32:33] op_sel_hi:[0,1,1]
	v_pk_mul_f32 v[12:13], v[10:11], v[10:11]
	s_nop 0
	v_add_f32_e32 v4, v156, v12
	v_add_f32_dpp v12, v51, v51 quad_perm:[1,0,3,2] row_mask:0xf bank_mask:0xf bound_ctrl:1
	v_add_f32_e32 v30, v4, v13
	v_add_u32_e32 v4, s12, v63
	v_add_f32_dpp v12, v12, v12 quad_perm:[2,3,0,1] row_mask:0xf bank_mask:0xf bound_ctrl:1
	v_mov_b32_e32 v51, v1
	s_nop 0
	v_add_f32_dpp v12, v12, v12 row_half_mirror row_mask:0xf bank_mask:0xf bound_ctrl:1
	s_nop 1
	v_add_f32_dpp v12, v12, v12 row_mirror row_mask:0xf bank_mask:0xf bound_ctrl:1
	v_fmamk_f32 v12, v12, 0x3c000000, v161
	v_cmp_gt_f32_e32 vcc, s13, v12
	v_mul_f32_e32 v13, 0x4b800000, v12
	s_nop 0
	v_cndmask_b32_e32 v12, v12, v13, vcc
	v_rsq_f32_e32 v12, v12
	s_nop 0
	v_mul_f32_e32 v13, 0x45800000, v12
	v_cndmask_b32_e32 v32, v12, v13, vcc
	v_mad_i64_i32 v[12:13], s[0:1], v4, s22, v[52:53]
	v_lshl_add_u64 v[12:13], v[12:13], 0, s[4:5]
	v_lshl_add_u64 v[12:13], v[12:13], 0, v[50:51]
	v_lshl_add_u64 v[156:157], v[12:13], 0, s[24:25]
	v_add_co_u32_e32 v12, vcc, s19, v12
	v_mul_f32_e32 v153, v153, v32
	s_nop 0
	v_addc_co_u32_e32 v13, vcc, 0, v13, vcc
	global_load_ushort v33, v[12:13], off offset:768
	global_load_ushort v226, v[156:157], off offset:32
	global_load_ushort v227, v[156:157], off offset:64
	global_load_ushort v228, v[156:157], off offset:96
	global_load_ushort v229, v[156:157], off offset:128
	global_load_ushort v230, v[156:157], off offset:160
	global_load_ushort v231, v[156:157], off offset:192
	global_load_ushort v232, v[156:157], off offset:224
	s_waitcnt vmcnt(7)
	v_lshlrev_b32_e32 v33, 16, v33
	v_mul_f32_e32 v153, v153, v33
	v_mul_f32_e32 v33, 0xbfb8aa3b, v33
	v_exp_f32_e32 v33, v33
	s_nop 0
	v_add_f32_e32 v33, 1.0, v33
	v_rcp_f32_e32 v33, v33
	s_nop 0
	v_mul_f32_e32 v33, v33, v153
	v_cvt_pk_bf16_f32 v33, v33, v1
	global_store_short v[12:13], v33, off offset:768
	v_mul_f32_e32 v13, v154, v32
	s_waitcnt vmcnt(7)
; __device__ __forceinline__ float bf2f(bf16_t b) { return __uint_as_float(((unsigned)b) << 16); }
; __device__ __forceinline__ bf16_t f2bf(float f) { return (bf16_t)(cvt_pk_bf16(f, 0.f) & 0xffffu); }
; __device__ __forceinline__ float allreduce16(float x) { x += dppf(x, 0); x += dppf(x, 1); x += dppf(x, 2); x += dppf(x, 3); return x; }
; __device__ __forceinline__ float sigmoidf_(float x) { return __builtin_amdgcn_rcpf(1.0f + __expf(-x)); }
; __device__ void ret_output(const Params& p, unsigned char* shm, int wg, int nwg) {
;     ...
;         for (int j = 0; j < 4; ++j) {
;             const float rs = rsqrtf(allreduce16(ss[j]) * (1.0f / 128.0f) + 1e-6f);
;             const int n = 16 * w + 4 * (lane >> 4) + j;
;             bf16_t* gp = Z + (size_t)(b * T + c * 128 + n) * ZLD + ZC_RET + 2304 + h * 128 + (lane & 15);
; #pragma unroll
;             for (int nt = 0; nt < 8; ++nt) { const float gv = bf2f(gp[16 * nt]); gp[16 * nt] = (ABL == 3) ? (bf16_t)0 : f2bf(oacc[nt][j] * rs * gv * sigmoidf_(gv)); }
	v_lshlrev_b32_e32 v12, 16, v226
	v_mul_f32_e32 v13, v13, v12
	v_mul_f32_e32 v12, 0xbfb8aa3b, v12
	v_exp_f32_e32 v12, v12
	s_nop 0
	v_add_f32_e32 v12, 1.0, v12
	v_rcp_f32_e32 v12, v12
	s_nop 0
	v_mul_f32_e32 v12, v12, v13
	v_cvt_pk_bf16_f32 v12, v12, v1
	global_store_short v[156:157], v12, off offset:32
	v_mul_f32_e32 v13, v34, v32
	s_waitcnt vmcnt(7)
	v_lshlrev_b32_e32 v12, 16, v227
	v_mul_f32_e32 v13, v13, v12
	v_mul_f32_e32 v12, 0xbfb8aa3b, v12
	v_exp_f32_e32 v12, v12
	s_nop 0
	v_add_f32_e32 v12, 1.0, v12
	v_rcp_f32_e32 v12, v12
	s_nop 0
	v_mul_f32_e32 v12, v13, v12
	v_cvt_pk_bf16_f32 v12, v12, v1
	global_store_short v[156:157], v12, off offset:64
	v_mul_f32_e32 v13, v35, v32
	s_waitcnt vmcnt(7)
	v_lshlrev_b32_e32 v12, 16, v228
	v_mul_f32_e32 v13, v13, v12
	v_mul_f32_e32 v12, 0xbfb8aa3b, v12
	v_exp_f32_e32 v12, v12
	s_nop 0
	v_add_f32_e32 v12, 1.0, v12
	v_rcp_f32_e32 v12, v12
	s_nop 0
	v_mul_f32_e32 v12, v13, v12
	v_cvt_pk_bf16_f32 v12, v12, v1
	global_store_short v[156:157], v12, off offset:96
	v_mul_f32_e32 v13, v28, v32
	s_waitcnt vmcnt(7)
	v_lshlrev_b32_e32 v12, 16, v229
	v_mul_f32_e32 v13, v13, v12
	v_mul_f32_e32 v12, 0xbfb8aa3b, v12
	v_exp_f32_e32 v12, v12
	s_nop 0
	v_add_f32_e32 v12, 1.0, v12
	v_rcp_f32_e32 v12, v12
	s_nop 0
	v_mul_f32_e32 v12, v13, v12
	v_cvt_pk_bf16_f32 v12, v12, v1
	global_store_short v[156:157], v12, off offset:128
	v_mul_f32_e32 v13, v29, v32
	s_waitcnt vmcnt(7)
	v_lshlrev_b32_e32 v12, 16, v230
	v_mul_f32_e32 v13, v13, v12
	v_mul_f32_e32 v12, 0xbfb8aa3b, v12
	v_exp_f32_e32 v12, v12
	s_nop 0
	v_add_f32_e32 v12, 1.0, v12
	v_rcp_f32_e32 v12, v12
	s_nop 0
	v_mul_f32_e32 v12, v13, v12
	v_cvt_pk_bf16_f32 v12, v12, v1
	global_store_short v[156:157], v12, off offset:160
	v_mul_f32_e32 v13, v24, v32
	s_waitcnt vmcnt(7)
	v_lshlrev_b32_e32 v12, 16, v231
	v_mul_f32_e32 v13, v13, v12
	v_mul_f32_e32 v12, 0xbfb8aa3b, v12
	v_exp_f32_e32 v12, v12
	s_nop 0
	v_add_f32_e32 v12, 1.0, v12
	v_rcp_f32_e32 v12, v12
	s_nop 0
	v_mul_f32_e32 v12, v13, v12
	v_cvt_pk_bf16_f32 v12, v12, v1
	global_store_short v[156:157], v12, off offset:192
	v_mul_f32_e32 v13, v25, v32
	s_waitcnt vmcnt(7)
	v_lshlrev_b32_e32 v12, 16, v232
	v_mul_f32_e32 v13, v13, v12
	v_mul_f32_e32 v12, 0xbfb8aa3b, v12
	v_exp_f32_e32 v12, v12
	s_nop 0
	v_add_f32_e32 v12, 1.0, v12
	v_rcp_f32_e32 v12, v12
	s_nop 0
	v_mul_f32_e32 v12, v13, v12
	v_cvt_pk_bf16_f32 v12, v12, v1
	global_store_short v[156:157], v12, off offset:224
	s_nop 0
	v_add_f32_dpp v12, v155, v155 quad_perm:[1,0,3,2] row_mask:0xf bank_mask:0xf bound_ctrl:1
	s_nop 1
	v_add_f32_dpp v12, v12, v12 quad_perm:[2,3,0,1] row_mask:0xf bank_mask:0xf bound_ctrl:1
	s_nop 1
	v_add_f32_dpp v12, v12, v12 row_half_mirror row_mask:0xf bank_mask:0xf bound_ctrl:1
	s_nop 1
	v_add_f32_dpp v12, v12, v12 row_mirror row_mask:0xf bank_mask:0xf bound_ctrl:1
	v_fmamk_f32 v12, v12, 0x3c000000, v161
	v_cmp_gt_f32_e32 vcc, s13, v12
	v_mul_f32_e32 v13, 0x4b800000, v12
	s_nop 0
	v_cndmask_b32_e32 v12, v12, v13, vcc
	v_rsq_f32_e32 v12, v12
	s_nop 0
	v_mul_f32_e32 v13, 0x45800000, v12
	v_cndmask_b32_e32 v12, v12, v13, vcc
	v_or_b32_e32 v13, 1, v4
	v_mad_i64_i32 v[24:25], s[0:1], v13, s22, v[52:53]
	v_lshl_add_u64 v[24:25], v[24:25], 0, s[4:5]
	v_lshl_add_u64 v[24:25], v[24:25], 0, v[50:51]
	v_lshl_add_u64 v[28:29], v[24:25], 0, s[24:25]
	v_add_co_u32_e32 v24, vcc, s19, v24
	v_mul_f32_e32 v32, v37, v12
	s_nop 0
	v_addc_co_u32_e32 v25, vcc, 0, v25, vcc
	global_load_ushort v13, v[24:25], off offset:768
	global_load_ushort v226, v[28:29], off offset:32
	global_load_ushort v227, v[28:29], off offset:64
	global_load_ushort v228, v[28:29], off offset:96
	global_load_ushort v229, v[28:29], off offset:128
	global_load_ushort v230, v[28:29], off offset:160
	global_load_ushort v231, v[28:29], off offset:192
	global_load_ushort v232, v[28:29], off offset:224
	v_mul_f32_e32 v22, v22, v12
	v_mul_f32_e32 v20, v20, v12
	s_waitcnt vmcnt(7)
	v_lshlrev_b32_e32 v13, 16, v13
	v_mul_f32_e32 v32, v32, v13
	v_mul_f32_e32 v13, 0xbfb8aa3b, v13
	v_exp_f32_e32 v13, v13
	s_nop 0
	v_add_f32_e32 v13, 1.0, v13
	v_rcp_f32_e32 v13, v13
	s_nop 0
	v_mul_f32_e32 v13, v13, v32
	v_cvt_pk_bf16_f32 v13, v13, v1
	global_store_short v[24:25], v13, off offset:768
	v_mul_f32_e32 v24, v152, v12
	s_waitcnt vmcnt(7)
	v_lshlrev_b32_e32 v13, 16, v226
	v_mul_f32_e32 v24, v24, v13
	v_mul_f32_e32 v13, 0xbfb8aa3b, v13
	v_exp_f32_e32 v13, v13
	s_nop 0
	v_add_f32_e32 v13, 1.0, v13
	v_rcp_f32_e32 v13, v13
	s_nop 0
	v_mul_f32_e32 v13, v24, v13
	v_cvt_pk_bf16_f32 v13, v13, v1
	global_store_short v[28:29], v13, off offset:32
	v_mul_f32_e32 v24, v26, v12
	s_waitcnt vmcnt(7)
	v_lshlrev_b32_e32 v13, 16, v227
	v_mul_f32_e32 v24, v24, v13
	v_mul_f32_e32 v13, 0xbfb8aa3b, v13
	v_exp_f32_e32 v13, v13
	s_nop 0
	v_add_f32_e32 v13, 1.0, v13
	v_rcp_f32_e32 v13, v13
	s_nop 0
	v_mul_f32_e32 v13, v24, v13
	v_cvt_pk_bf16_f32 v13, v13, v1
	global_store_short v[28:29], v13, off offset:64
	v_mul_f32_e32 v24, v27, v12
	s_waitcnt vmcnt(7)
	v_lshlrev_b32_e32 v13, 16, v228
	v_mul_f32_e32 v24, v24, v13
	v_mul_f32_e32 v13, 0xbfb8aa3b, v13
	v_exp_f32_e32 v13, v13
	s_nop 0
	v_add_f32_e32 v13, 1.0, v13
	v_rcp_f32_e32 v13, v13
	s_nop 0
	v_mul_f32_e32 v13, v24, v13
	v_cvt_pk_bf16_f32 v13, v13, v1
	global_store_short v[28:29], v13, off offset:96
	s_waitcnt vmcnt(7)
	v_lshlrev_b32_e32 v13, 16, v229
	v_mul_f32_e32 v22, v22, v13
	v_mul_f32_e32 v13, 0xbfb8aa3b, v13
	v_exp_f32_e32 v13, v13
	s_nop 0
	v_add_f32_e32 v13, 1.0, v13
	v_rcp_f32_e32 v13, v13
	s_nop 0
	v_mul_f32_e32 v13, v22, v13
	v_cvt_pk_bf16_f32 v13, v13, v1
	global_store_short v[28:29], v13, off offset:128
	v_mul_f32_e32 v22, v23, v12
	v_mul_f32_e32 v12, v21, v12
	s_waitcnt vmcnt(7)
; __device__ __forceinline__ float bf2f(bf16_t b) { return __uint_as_float(((unsigned)b) << 16); }
; __device__ __forceinline__ bf16_t f2bf(float f) { return (bf16_t)(cvt_pk_bf16(f, 0.f) & 0xffffu); }
; __device__ __forceinline__ float allreduce16(float x) { x += dppf(x, 0); x += dppf(x, 1); x += dppf(x, 2); x += dppf(x, 3); return x; }
; __device__ __forceinline__ float sigmoidf_(float x) { return __builtin_amdgcn_rcpf(1.0f + __expf(-x)); }
; __device__ void ret_output(const Params& p, unsigned char* shm, int wg, int nwg) {
;     ...
;         for (int j = 0; j < 4; ++j) {
;             const float rs = rsqrtf(allreduce16(ss[j]) * (1.0f / 128.0f) + 1e-6f);
;             const int n = 16 * w + 4 * (lane >> 4) + j;
;             bf16_t* gp = Z + (size_t)(b * T + c * 128 + n) * ZLD + ZC_RET + 2304 + h * 128 + (lane & 15);
; #pragma unroll
;             for (int nt = 0; nt < 8; ++nt) { const float gv = bf2f(gp[16 * nt]); gp[16 * nt] = (ABL == 3) ? (bf16_t)0 : f2bf(oacc[nt][j] * rs * gv * sigmoidf_(gv)); }
	v_lshlrev_b32_e32 v13, 16, v230
	v_mul_f32_e32 v22, v22, v13
	v_mul_f32_e32 v13, 0xbfb8aa3b, v13
	v_exp_f32_e32 v13, v13
	s_nop 0
	v_add_f32_e32 v13, 1.0, v13
	v_rcp_f32_e32 v13, v13
	s_nop 0
	v_mul_f32_e32 v13, v22, v13
	v_cvt_pk_bf16_f32 v13, v13, v1
	global_store_short v[28:29], v13, off offset:160
	s_waitcnt vmcnt(7)
	v_lshlrev_b32_e32 v13, 16, v231
	v_mul_f32_e32 v20, v20, v13
	v_mul_f32_e32 v13, 0xbfb8aa3b, v13
	v_exp_f32_e32 v13, v13
	s_nop 0
	v_add_f32_e32 v13, 1.0, v13
	v_rcp_f32_e32 v13, v13
	s_nop 0
	v_mul_f32_e32 v13, v20, v13
	v_cvt_pk_bf16_f32 v13, v13, v1
	global_store_short v[28:29], v13, off offset:192
	s_waitcnt vmcnt(7)
	v_lshlrev_b32_e32 v13, 16, v232
	v_mul_f32_e32 v12, v12, v13
	v_mul_f32_e32 v13, 0xbfb8aa3b, v13
	v_exp_f32_e32 v13, v13
	s_nop 0
	v_add_f32_e32 v13, 1.0, v13
	v_rcp_f32_e32 v13, v13
	s_nop 0
	v_mul_f32_e32 v12, v12, v13
	v_cvt_pk_bf16_f32 v12, v12, v1
	global_store_short v[28:29], v12, off offset:224
	s_nop 0
	v_add_f32_dpp v12, v31, v31 quad_perm:[1,0,3,2] row_mask:0xf bank_mask:0xf bound_ctrl:1
	s_nop 1
	v_add_f32_dpp v12, v12, v12 quad_perm:[2,3,0,1] row_mask:0xf bank_mask:0xf bound_ctrl:1
	s_nop 1
	v_add_f32_dpp v12, v12, v12 row_half_mirror row_mask:0xf bank_mask:0xf bound_ctrl:1
	s_nop 1
	v_add_f32_dpp v12, v12, v12 row_mirror row_mask:0xf bank_mask:0xf bound_ctrl:1
	v_fmamk_f32 v12, v12, 0x3c000000, v161
	v_cmp_gt_f32_e32 vcc, s13, v12
	v_mul_f32_e32 v13, 0x4b800000, v12
	s_nop 0
	v_cndmask_b32_e32 v12, v12, v13, vcc
	v_rsq_f32_e32 v12, v12
	s_nop 0
	v_mul_f32_e32 v13, 0x45800000, v12
	v_cndmask_b32_e32 v12, v12, v13, vcc
	v_or_b32_e32 v13, 2, v4
	v_mad_i64_i32 v[20:21], s[0:1], v13, s22, v[52:53]
	v_lshl_add_u64 v[20:21], v[20:21], 0, s[4:5]
	v_lshl_add_u64 v[20:21], v[20:21], 0, v[50:51]
	v_lshl_add_u64 v[22:23], v[20:21], 0, s[24:25]
	v_add_co_u32_e32 v20, vcc, s19, v20
	v_mul_f32_e32 v8, v8, v12
	s_nop 0
	v_addc_co_u32_e32 v21, vcc, 0, v21, vcc
	global_load_ushort v13, v[20:21], off offset:768
	global_load_ushort v226, v[22:23], off offset:32
	global_load_ushort v227, v[22:23], off offset:64
	global_load_ushort v228, v[22:23], off offset:96
	global_load_ushort v229, v[22:23], off offset:128
	global_load_ushort v230, v[22:23], off offset:160
	global_load_ushort v231, v[22:23], off offset:192
	global_load_ushort v232, v[22:23], off offset:224
	v_or_b32_e32 v4, 3, v4
	s_waitcnt vmcnt(7)
	v_lshlrev_b32_e32 v13, 16, v13
	v_mul_f32_e32 v8, v8, v13
	v_mul_f32_e32 v13, 0xbfb8aa3b, v13
	v_exp_f32_e32 v13, v13
	s_nop 0
	v_add_f32_e32 v13, 1.0, v13
	v_rcp_f32_e32 v13, v13
	s_nop 0
	v_mul_f32_e32 v8, v13, v8
	v_cvt_pk_bf16_f32 v8, v8, v1
	global_store_short v[20:21], v8, off offset:768
	v_mul_f32_e32 v13, v36, v12
	s_waitcnt vmcnt(7)
	v_lshlrev_b32_e32 v8, 16, v226
	v_mul_f32_e32 v13, v13, v8
	v_mul_f32_e32 v8, 0xbfb8aa3b, v8
	v_exp_f32_e32 v8, v8
	s_nop 0
	v_add_f32_e32 v8, 1.0, v8
	v_rcp_f32_e32 v8, v8
	s_nop 0
	v_mul_f32_e32 v8, v13, v8
	v_cvt_pk_bf16_f32 v8, v8, v1
	global_store_short v[22:23], v8, off offset:32
	v_mul_f32_e32 v13, v14, v12
	s_waitcnt vmcnt(7)
	v_lshlrev_b32_e32 v8, 16, v227
	v_mul_f32_e32 v13, v13, v8
	v_mul_f32_e32 v8, 0xbfb8aa3b, v8
	v_exp_f32_e32 v8, v8
	s_nop 0
	v_add_f32_e32 v8, 1.0, v8
	v_rcp_f32_e32 v8, v8
	s_nop 0
	v_mul_f32_e32 v8, v13, v8
	v_cvt_pk_bf16_f32 v8, v8, v1
	global_store_short v[22:23], v8, off offset:64
	v_mul_f32_e32 v13, v15, v12
	s_waitcnt vmcnt(7)
	v_lshlrev_b32_e32 v8, 16, v228
	v_mul_f32_e32 v13, v13, v8
	v_mul_f32_e32 v8, 0xbfb8aa3b, v8
	v_exp_f32_e32 v8, v8
	s_nop 0
	v_add_f32_e32 v8, 1.0, v8
	v_rcp_f32_e32 v8, v8
	s_nop 0
	v_mul_f32_e32 v8, v13, v8
	v_cvt_pk_bf16_f32 v8, v8, v1
	global_store_short v[22:23], v8, off offset:96
	v_mul_f32_e32 v13, v16, v12
	s_waitcnt vmcnt(7)
	v_lshlrev_b32_e32 v8, 16, v229
	v_mul_f32_e32 v13, v13, v8
	v_mul_f32_e32 v8, 0xbfb8aa3b, v8
	v_exp_f32_e32 v8, v8
	s_nop 0
	v_add_f32_e32 v8, 1.0, v8
	v_rcp_f32_e32 v8, v8
	s_nop 0
	v_mul_f32_e32 v8, v13, v8
	v_cvt_pk_bf16_f32 v8, v8, v1
	global_store_short v[22:23], v8, off offset:128
	v_mul_f32_e32 v13, v17, v12
	s_waitcnt vmcnt(7)
	v_lshlrev_b32_e32 v8, 16, v230
	v_mul_f32_e32 v13, v13, v8
	v_mul_f32_e32 v8, 0xbfb8aa3b, v8
	v_exp_f32_e32 v8, v8
	s_nop 0
	v_add_f32_e32 v8, 1.0, v8
	v_rcp_f32_e32 v8, v8
	s_nop 0
	v_mul_f32_e32 v8, v13, v8
	v_cvt_pk_bf16_f32 v8, v8, v1
	global_store_short v[22:23], v8, off offset:160
	v_mul_f32_e32 v13, v18, v12
	v_mul_f32_e32 v12, v19, v12
	s_waitcnt vmcnt(7)
; __device__ __forceinline__ float bf2f(bf16_t b) { return __uint_as_float(((unsigned)b) << 16); }
; __device__ __forceinline__ bf16_t f2bf(float f) { return (bf16_t)(cvt_pk_bf16(f, 0.f) & 0xffffu); }
; __device__ __forceinline__ float allreduce16(float x) { x += dppf(x, 0); x += dppf(x, 1); x += dppf(x, 2); x += dppf(x, 3); return x; }
; __device__ __forceinline__ float sigmoidf_(float x) { return __builtin_amdgcn_rcpf(1.0f + __expf(-x)); }
; __device__ void ret_output(const Params& p, unsigned char* shm, int wg, int nwg) {
;     ...
;         for (int j = 0; j < 4; ++j) {
;             const float rs = rsqrtf(allreduce16(ss[j]) * (1.0f / 128.0f) + 1e-6f);
;             const int n = 16 * w + 4 * (lane >> 4) + j;
;             bf16_t* gp = Z + (size_t)(b * T + c * 128 + n) * ZLD + ZC_RET + 2304 + h * 128 + (lane & 15);
; #pragma unroll
;             for (int nt = 0; nt < 8; ++nt) { const float gv = bf2f(gp[16 * nt]); gp[16 * nt] = (ABL == 3) ? (bf16_t)0 : f2bf(oacc[nt][j] * rs * gv * sigmoidf_(gv)); }
;         }
;         __syncthreads();
	v_lshlrev_b32_e32 v8, 16, v231
	v_mul_f32_e32 v13, v13, v8
	v_mul_f32_e32 v8, 0xbfb8aa3b, v8
	v_exp_f32_e32 v8, v8
	s_nop 0
	v_add_f32_e32 v8, 1.0, v8
	v_rcp_f32_e32 v8, v8
	s_nop 0
	v_mul_f32_e32 v8, v13, v8
	v_cvt_pk_bf16_f32 v8, v8, v1
	global_store_short v[22:23], v8, off offset:192
	s_waitcnt vmcnt(7)
	v_lshlrev_b32_e32 v8, 16, v232
	v_mul_f32_e32 v12, v12, v8
	v_mul_f32_e32 v8, 0xbfb8aa3b, v8
	v_exp_f32_e32 v8, v8
	s_nop 0
	v_add_f32_e32 v8, 1.0, v8
	v_rcp_f32_e32 v8, v8
	s_nop 0
	v_mul_f32_e32 v8, v12, v8
	v_cvt_pk_bf16_f32 v8, v8, v1
	global_store_short v[22:23], v8, off offset:224
	s_nop 0
	v_add_f32_dpp v8, v30, v30 quad_perm:[1,0,3,2] row_mask:0xf bank_mask:0xf bound_ctrl:1
	s_nop 1
	v_add_f32_dpp v8, v8, v8 quad_perm:[2,3,0,1] row_mask:0xf bank_mask:0xf bound_ctrl:1
	s_nop 1
	v_add_f32_dpp v8, v8, v8 row_half_mirror row_mask:0xf bank_mask:0xf bound_ctrl:1
	s_nop 1
	v_add_f32_dpp v8, v8, v8 row_mirror row_mask:0xf bank_mask:0xf bound_ctrl:1
	v_fmamk_f32 v8, v8, 0x3c000000, v161
	v_cmp_gt_f32_e32 vcc, s13, v8
	v_mul_f32_e32 v12, 0x4b800000, v8
	s_nop 0
	v_cndmask_b32_e32 v8, v8, v12, vcc
	v_rsq_f32_e32 v8, v8
	s_nop 0
	v_mul_f32_e32 v12, 0x45800000, v8
	v_cndmask_b32_e32 v8, v8, v12, vcc
	v_mad_i64_i32 v[12:13], s[0:1], v4, s22, v[52:53]
	v_lshl_add_u64 v[12:13], v[12:13], 0, s[4:5]
	v_lshl_add_u64 v[12:13], v[12:13], 0, v[50:51]
	v_lshl_add_u64 v[14:15], v[12:13], 0, s[24:25]
	v_add_co_u32_e32 v12, vcc, s19, v12
	v_mul_f32_e32 v9, v9, v8
	s_nop 0
	v_addc_co_u32_e32 v13, vcc, 0, v13, vcc
	global_load_ushort v4, v[12:13], off offset:768
	global_load_ushort v226, v[14:15], off offset:32
	global_load_ushort v227, v[14:15], off offset:64
	global_load_ushort v228, v[14:15], off offset:96
	global_load_ushort v229, v[14:15], off offset:128
	global_load_ushort v230, v[14:15], off offset:160
	global_load_ushort v231, v[14:15], off offset:192
	global_load_ushort v232, v[14:15], off offset:224
	v_mul_f32_e32 v5, v5, v8
	v_mul_f32_e32 v2, v2, v8
	v_mul_f32_e32 v3, v3, v8
	s_waitcnt vmcnt(7)
	v_lshlrev_b32_e32 v4, 16, v4
	v_mul_f32_e32 v9, v9, v4
	v_mul_f32_e32 v4, 0xbfb8aa3b, v4
	v_exp_f32_e32 v4, v4
	s_nop 0
	v_add_f32_e32 v4, 1.0, v4
	v_rcp_f32_e32 v4, v4
	s_nop 0
	v_mul_f32_e32 v4, v4, v9
	v_cvt_pk_bf16_f32 v4, v4, v1
	global_store_short v[12:13], v4, off offset:768
	s_waitcnt vmcnt(7)
	v_lshlrev_b32_e32 v4, 16, v226
	v_mul_f32_e32 v5, v5, v4
	v_mul_f32_e32 v4, 0xbfb8aa3b, v4
	v_exp_f32_e32 v4, v4
	s_nop 0
	v_add_f32_e32 v4, 1.0, v4
	v_rcp_f32_e32 v4, v4
	s_nop 0
	v_mul_f32_e32 v4, v5, v4
	v_cvt_pk_bf16_f32 v4, v4, v1
	global_store_short v[14:15], v4, off offset:32
	s_waitcnt vmcnt(7)
	v_lshlrev_b32_e32 v4, 16, v227
	v_mul_f32_e32 v2, v2, v4
	v_mul_f32_e32 v4, 0xbfb8aa3b, v4
	v_exp_f32_e32 v4, v4
	s_nop 0
	v_add_f32_e32 v4, 1.0, v4
	v_rcp_f32_e32 v4, v4
	s_nop 0
	v_mul_f32_e32 v2, v2, v4
	v_cvt_pk_bf16_f32 v2, v2, v1
	global_store_short v[14:15], v2, off offset:64
	s_waitcnt vmcnt(7)
	v_lshlrev_b32_e32 v2, 16, v228
	v_mul_f32_e32 v3, v3, v2
	v_mul_f32_e32 v2, 0xbfb8aa3b, v2
	v_exp_f32_e32 v2, v2
	s_nop 0
	v_add_f32_e32 v2, 1.0, v2
	v_rcp_f32_e32 v2, v2
	s_nop 0
	v_mul_f32_e32 v2, v3, v2
	v_cvt_pk_bf16_f32 v2, v2, v1
	global_store_short v[14:15], v2, off offset:96
	v_mul_f32_e32 v3, v6, v8
	s_waitcnt vmcnt(7)
	v_lshlrev_b32_e32 v2, 16, v229
	v_mul_f32_e32 v3, v3, v2
	v_mul_f32_e32 v2, 0xbfb8aa3b, v2
	v_exp_f32_e32 v2, v2
	s_nop 0
	v_add_f32_e32 v2, 1.0, v2
	v_rcp_f32_e32 v2, v2
	s_nop 0
	v_mul_f32_e32 v2, v3, v2
	v_cvt_pk_bf16_f32 v2, v2, v1
	global_store_short v[14:15], v2, off offset:128
	v_mul_f32_e32 v3, v7, v8
	s_waitcnt vmcnt(7)
	v_lshlrev_b32_e32 v2, 16, v230
	v_mul_f32_e32 v3, v3, v2
	v_mul_f32_e32 v2, 0xbfb8aa3b, v2
	v_exp_f32_e32 v2, v2
	s_nop 0
	v_add_f32_e32 v2, 1.0, v2
	v_rcp_f32_e32 v2, v2
	s_nop 0
	v_mul_f32_e32 v2, v3, v2
	v_cvt_pk_bf16_f32 v2, v2, v1
	global_store_short v[14:15], v2, off offset:160
	v_mul_f32_e32 v3, v10, v8
	s_waitcnt vmcnt(7)
	v_lshlrev_b32_e32 v2, 16, v231
	v_mul_f32_e32 v3, v3, v2
	v_mul_f32_e32 v2, 0xbfb8aa3b, v2
	v_exp_f32_e32 v2, v2
	s_nop 0
	v_add_f32_e32 v2, 1.0, v2
	v_rcp_f32_e32 v2, v2
	s_nop 0
	v_mul_f32_e32 v2, v3, v2
	v_cvt_pk_bf16_f32 v2, v2, v1
	global_store_short v[14:15], v2, off offset:192
	v_mul_f32_e32 v3, v11, v8
	s_waitcnt vmcnt(7)
	v_lshlrev_b32_e32 v2, 16, v232
	v_mul_f32_e32 v3, v3, v2
	v_mul_f32_e32 v2, 0xbfb8aa3b, v2
	v_exp_f32_e32 v2, v2
	s_nop 0
	v_add_f32_e32 v2, 1.0, v2
	v_rcp_f32_e32 v2, v2
	s_nop 0
	v_mul_f32_e32 v2, v3, v2
	v_cvt_pk_bf16_f32 v2, v2, v1
	global_store_short v[14:15], v2, off offset:224
	s_barrier
	s_cbranch_scc1 .LBB0_135
	s_mov_b32 s52, 0x800000

; __device__ __forceinline__ int otid() { int t = threadIdx.x; asm volatile("" : "+v"(t)); return t; }
; __device__ __forceinline__ void na_phase(const Params& p, int l, unsigned char* shm, int item_lo, int item_hi, int wg, int nwg) {
;     bf16_t* Z = (bf16_t*)(p.ws + WS_Z);
;     const float* rpb = p.in[3] + (size_t)l * 8 * 15 * 31;
;     const int tid = otid(), w = tid >> 6, lane = tid & 63, n_ = lane & 15, kg = lane >> 4;
;     unsigned char* Ks = shm;
;     unsigned char* Vt = shm + 73728;
;     float* red = (float*)(shm + 140288);
;     float* brow = red + 512;
;     for (int item = item_lo + wg; item < item_hi; item += nwg) {
;         const int h = item & 7, i = (item >> 3) & 255, b = item >> 11;
;         const int s0 = min(max(i - 4, 0), 248);
;         bf16x8 qf[4][2];
; #pragma unroll
;         for (int mt = 0; mt < 4; ++mt)
; #pragma unroll
;             for (int ks = 0; ks < 2; ++ks) qf[mt][ks] = *(const bf16x8*)(Z + (size_t)(b * T + i * 64 + 16 * mt + n_) * ZLD + ZC_NAQ + h * 64 + 32 * ks + 8 * kg);
; #pragma unroll
;         for (int it = 0; it < 8; ++it) { const int idx = it * NTHR + tid, key = idx >> 3, ch = idx & 7;
;             const size_t tok = (size_t)b * T + (size_t)(s0 + (key >> 6)) * 64 + (key & 63);
;             *(u32x4*)(Ks + key * 144 + ch * 16) = *(const u32x4*)(Z + tok * ZLD + ZC_NAK + h * 64 + ch * 8); }
;         { const size_t tok = (size_t)b * T + (size_t)(s0 + (tid >> 6)) * 64 + (tid & 63);
; #pragma unroll
;           for (int it = 0; it < 8; ++it) { const u32x4 v4 = *(const u32x4*)(Z + tok * ZLD + ZC_NAV + h * 64 + it * 8); const unsigned vv[4] = {v4.x, v4.y, v4.z, v4.w};
; #pragma unroll
;               for (int e = 0; e < 4; ++e) { *(bf16_t*)(Vt + (it * 8 + 2 * e) * 1040 + tid * 2) = (bf16_t)(vv[e] & 0xffffu); *(bf16_t*)(Vt + (it * 8 + 2 * e + 1) * 1040 + tid * 2) = (bf16_t)(vv[e] >> 16); } } }
;         if (lane < 31) brow[w * 32 + lane] = rpb[(size_t)h * 15 * 31 + (size_t)(s0 + w - i + 7) * 31 + lane];
.LBB0_146:
	v_writelane_b32 v254, s46, 63
	v_mov_b32_e32 v5, v160
	s_cmpk_gt_i32 s8, 0xebf
	v_writelane_b32 v252, s47, 0
	s_barrier
	s_cbranch_scc1 .LBB0_295
	v_readlane_b32 s0, v254, 63
	v_readlane_b32 s1, v252, 0
	s_mov_b32 s2, s0
	v_readlane_b32 s36, v254, 9
	s_mul_i32 s1, s2, 0x3a20
	v_readlane_b32 s42, v254, 15
	v_ashrrev_i32_e32 v47, 6, v5
	v_and_b32_e32 v2, 48, v5
	v_mov_b32_e32 v3, v1
	v_and_b32_e32 v0, 7, v5
	s_mul_hi_i32 s0, s0, 0x3a20
	v_readlane_b32 s43, v254, 16
	s_add_u32 s2, s42, s1
	v_bfe_u32 v8, v5, 4, 2
	v_lshl_add_u64 v[48:49], s[78:79], 0, v[2:3]
	s_waitcnt vmcnt(4)
	v_lshlrev_b32_e32 v6, 3, v0
	v_lshl_add_u32 v3, v0, 4, 0
	v_and_b32_e32 v0, 3, v47
	s_addc_u32 s3, s43, s0
	v_and_b32_e32 v53, 15, v5
	s_add_i32 s23, s8, 0x140
	v_lshlrev_b32_e32 v12, 2, v8
	v_cmp_ne_u32_e64 s[6:7], 0, v0
	v_cmp_ne_u32_e64 s[8:9], 3, v0
	v_lshlrev_b32_e32 v0, 4, v0
	v_or_b32_e32 v4, v0, v53
	v_or_b32_e32 v57, v0, v12
	v_lshlrev_b32_e32 v0, 1, v53
	v_lshl_add_u64 v[50:51], s[78:79], 0, v[0:1]
	v_add_u32_e32 v0, 0x200, v5
	v_ashrrev_i32_e32 v19, 3, v0
	v_ashrrev_i32_e32 v61, 9, v0
	v_add_u32_e32 v0, 0x400, v5
	v_ashrrev_i32_e32 v20, 3, v0
	v_ashrrev_i32_e32 v63, 9, v0
	v_add_u32_e32 v0, 0x600, v5
	v_ashrrev_i32_e32 v21, 3, v0
	v_ashrrev_i32_e32 v65, 9, v0
	v_add_u32_e32 v0, 0x800, v5
	v_ashrrev_i32_e32 v22, 3, v0
	v_ashrrev_i32_e32 v67, 9, v0
	v_add_u32_e32 v0, 0xa00, v5
	v_ashrrev_i32_e32 v23, 3, v0
	v_ashrrev_i32_e32 v70, 9, v0
	v_add_u32_e32 v0, 0xc00, v5
	v_writelane_b32 v252, s2, 1
	v_and_b32_e32 v46, 63, v5
	v_readlane_b32 s0, v253, 42
	v_lshlrev_b32_e32 v9, 7, v47
	v_ashrrev_i32_e32 v24, 3, v0
	v_ashrrev_i32_e32 v71, 9, v0
	v_add_u32_e32 v0, 0xe00, v5
	v_writelane_b32 v252, s3, 2
	v_lshl_add_u32 v7, v46, 2, s0
	v_lshlrev_b32_e32 v55, 1, v5
	v_cmp_gt_u32_e64 s[2:3], 31, v46
	v_and_b32_e32 v10, 0xfffffcf, v5
	v_add_u32_e32 v13, s0, v9
	v_and_b32_e32 v14, 0xffffffc0, v5
	s_movk_i32 s26, 0x410
	v_ashrrev_i32_e32 v17, 3, v5
	v_ashrrev_i32_e32 v59, 9, v5
	s_movk_i32 s0, 0x90
	v_ashrrev_i32_e32 v25, 3, v0
	v_ashrrev_i32_e32 v72, 9, v0
	v_or_b32_e32 v0, 48, v5
	v_sub_u32_e64 v5, v12, 8 clamp
	v_readlane_b32 s37, v254, 10
	v_readlane_b32 s38, v254, 11
	v_readlane_b32 s39, v254, 12
	v_readlane_b32 s40, v254, 13
	v_readlane_b32 s41, v254, 14
	v_readlane_b32 s44, v254, 17
	v_readlane_b32 s45, v254, 18
	v_readlane_b32 s46, v254, 19
	v_readlane_b32 s47, v254, 20
	v_readlane_b32 s48, v254, 21
	v_readlane_b32 s49, v254, 22
	v_readlane_b32 s50, v254, 23
	v_readlane_b32 s51, v254, 24
	v_writelane_b32 v254, s2, 41
	v_mad_u32_u24 v16, v4, s26, 0
	v_and_b32_e32 v4, 0xffffffe0, v17
	v_and_b32_e32 v52, 63, v17
	v_mul_lo_u32 v17, v17, s0
	v_and_b32_e32 v54, 63, v19
	v_mul_lo_u32 v19, v19, s0
	v_and_b32_e32 v56, 63, v20
	v_mul_lo_u32 v20, v20, s0
	v_and_b32_e32 v58, 63, v21
	v_mul_lo_u32 v21, v21, s0
	v_and_b32_e32 v60, 63, v22
	v_mul_lo_u32 v22, v22, s0
	v_and_b32_e32 v62, 63, v23
	v_mul_lo_u32 v23, v23, s0
	v_and_b32_e32 v64, 63, v24
	v_mul_lo_u32 v24, v24, s0
	v_and_b32_e32 v66, 63, v25
	v_mul_lo_u32 v25, v25, s0
	v_mul_lo_u32 v10, v10, s0
	v_mul_lo_u32 v26, v0, s0
	v_cmp_ge_u32_e64 s[0:1], v53, v5
	v_sub_u32_e32 v5, v53, v12
	v_writelane_b32 v254, s3, 42
	v_lshl_add_u32 v74, v5, 2, v13
	v_or_b32_e32 v5, 1, v12
	v_writelane_b32 v254, s0, 43
	v_sub_u32_e64 v27, v5, 8 clamp
	v_mul_u32_u24_e32 v75, 0x1040, v8
	v_writelane_b32 v254, s1, 44
	v_max_u32_e32 v8, 8, v5
	v_cmp_ge_u32_e64 s[0:1], v53, v27
	v_sub_u32_e32 v27, v53, v5
	v_mul_u32_u24_e32 v77, 0x410, v5
	v_or_b32_e32 v5, 2, v12
	v_writelane_b32 v254, s0, 45
	v_lshl_add_u32 v76, v27, 2, v13
	v_max_u32_e32 v27, 8, v5
	v_sub_u32_e64 v28, v5, 8 clamp
	v_sub_u32_e32 v5, v53, v5
	v_writelane_b32 v254, s1, 46
	v_cmp_ge_u32_e64 s[0:1], v53, v28
	v_lshl_add_u32 v78, v5, 2, v13
	v_or_b32_e32 v5, 3, v12
	v_and_b32_e32 v0, 0xffffff9e, v55
	v_writelane_b32 v254, s0, 47
	v_sub_u32_e64 v29, v5, 8 clamp
	v_add_u32_e32 v73, 0, v0
	v_max_u32_e32 v0, 8, v12
	v_writelane_b32 v254, s1, 48
	v_max_u32_e32 v28, 8, v5
	v_cmp_ge_u32_e64 s[0:1], v53, v29
	v_sub_u32_e32 v5, v53, v5
	v_add_u32_e32 v0, 8, v0
	v_writelane_b32 v254, s0, 49
	v_lshl_add_u32 v79, v5, 2, v13
	v_or_b32_e32 v5, 16, v53
	v_writelane_b32 v254, s1, 50
	v_cmp_lt_u32_e64 s[0:1], v5, v0
	v_add_u32_e32 v8, 8, v8
	v_add_u32_e32 v27, 8, v27
	v_writelane_b32 v254, s0, 51
	v_add_u32_e32 v28, 8, v28
	v_readlane_b32 s25, v253, 43
	v_writelane_b32 v254, s1, 52
	v_cmp_lt_u32_e64 s[0:1], v5, v8
	v_or_b32_e32 v8, 32, v53
	v_or_b32_e32 v0, v8, v14
	v_writelane_b32 v254, s0, 53
	v_lshl_add_u32 v81, v0, 1, 0
	v_lshl_add_u32 v15, v14, 2, s25
	v_writelane_b32 v254, s1, 54
	v_cmp_lt_u32_e64 s[0:1], v5, v27
	v_or_b32_e32 v27, 48, v53
	v_or_b32_e32 v0, v27, v14
	v_writelane_b32 v254, s0, 55
	v_or_b32_e32 v29, v5, v14
	v_lshl_add_u32 v82, v0, 1, 0
	v_writelane_b32 v254, s1, 56
	v_cmp_lt_u32_e64 s[0:1], v5, v28
	v_or_b32_e32 v0, 16, v12
	v_add_u32_e32 v14, 8, v12
	v_writelane_b32 v254, s0, 57
	v_lshl_add_u32 v80, v29, 1, 0
	v_sub_u32_e32 v29, v53, v0
	v_writelane_b32 v254, s1, 58
	v_cmp_ge_u32_e64 s[0:1], v53, v14
	v_mul_u32_u24_e32 v84, 0x410, v0
	v_or_b32_e32 v0, 17, v12
	v_writelane_b32 v254, s0, 59
	v_lshl_add_u32 v83, v29, 2, v13
; __device__ __forceinline__ int otid() { int t = threadIdx.x; asm volatile("" : "+v"(t)); return t; }
; __device__ __forceinline__ void na_phase(const Params& p, int l, unsigned char* shm, int item_lo, int item_hi, int wg, int nwg) {
;     ...
;     const int tid = otid(), w = tid >> 6, lane = tid & 63, n_ = lane & 15, kg = lane >> 4;
;     unsigned char* Ks = shm;
;     unsigned char* Vt = shm + 73728;
;     float* red = (float*)(shm + 140288);
;     float* brow = red + 512;
;     for (int item = item_lo + wg; item < item_hi; item += nwg) {
;         const int h = item & 7, i = (item >> 3) & 255, b = item >> 11;
;         const int s0 = min(max(i - 4, 0), 248);
;         bf16x8 qf[4][2];
; #pragma unroll
;         for (int mt = 0; mt < 4; ++mt)
; #pragma unroll
;             for (int ks = 0; ks < 2; ++ks) qf[mt][ks] = *(const bf16x8*)(Z + (size_t)(b * T + i * 64 + 16 * mt + n_) * ZLD + ZC_NAQ + h * 64 + 32 * ks + 8 * kg);
; #pragma unroll
;         for (int it = 0; it < 8; ++it) { const int idx = it * NTHR + tid, key = idx >> 3, ch = idx & 7;
;             const size_t tok = (size_t)b * T + (size_t)(s0 + (key >> 6)) * 64 + (key & 63);
;             *(u32x4*)(Ks + key * 144 + ch * 16) = *(const u32x4*)(Z + tok * ZLD + ZC_NAK + h * 64 + ch * 8); }
;         { const size_t tok = (size_t)b * T + (size_t)(s0 + (tid >> 6)) * 64 + (tid & 63);
; #pragma unroll
;           for (int it = 0; it < 8; ++it) { const u32x4 v4 = *(const u32x4*)(Z + tok * ZLD + ZC_NAV + h * 64 + it * 8); const unsigned vv[4] = {v4.x, v4.y, v4.z, v4.w};
; #pragma unroll
;               for (int e = 0; e < 4; ++e) { *(bf16_t*)(Vt + (it * 8 + 2 * e) * 1040 + tid * 2) = (bf16_t)(vv[e] & 0xffffu); *(bf16_t*)(Vt + (it * 8 + 2 * e + 1) * 1040 + tid * 2) = (bf16_t)(vv[e] >> 16); } } }
;         if (lane < 31) brow[w * 32 + lane] = rpb[(size_t)h * 15 * 31 + (size_t)(s0 + w - i + 7) * 31 + lane];
;     ...
;                 for (int i2 = 0; i2 < 4; ++i2) { const int q = 16 * mt + 4 * kg + i2, col = 16 * nt + n_, cs = min(max(q - 8, 0), 48); const bool ok = (col >= cs) && (col < cs + 16);
;                     const float s = acc[mt][nt][i2] * 0.125f + brow[w * 32 + (ok ? col - q + 15 : 0)];
	v_add_u32_e32 v29, 9, v12
	v_sub_u32_e32 v0, v53, v0
	v_writelane_b32 v254, s1, 60
	v_cmp_ge_u32_e64 s[0:1], v53, v29
	v_lshl_add_u32 v85, v0, 2, v13
	v_or_b32_e32 v0, 18, v12
	v_writelane_b32 v254, s0, 61
	v_add_u32_e32 v31, 10, v12
	v_sub_u32_e32 v0, v53, v0
	v_writelane_b32 v254, s1, 62
	v_cmp_ge_u32_e64 s[0:1], v53, v31
	v_lshl_add_u32 v86, v0, 2, v13
	v_or_b32_e32 v0, 19, v12
	v_add_u32_e32 v28, 24, v12
	v_writelane_b32 v254, s0, 39
	v_sub_u32_e32 v0, v53, v0
	v_add_u32_e32 v30, 25, v12
	v_writelane_b32 v254, s1, 40
	v_lshl_add_u32 v87, v0, 2, v13
	v_cmp_ge_u32_e32 vcc, v5, v14
	v_cmp_lt_u32_e64 s[0:1], v5, v28
	v_or_b32_e32 v0, 32, v12
	v_add_u32_e32 v32, 26, v12
	s_and_b64 s[2:3], vcc, s[0:1]
	v_cmp_ge_u32_e32 vcc, v5, v29
	v_cmp_lt_u32_e64 s[0:1], v5, v30
	v_mul_u32_u24_e32 v88, 0x410, v0
	v_or_b32_e32 v14, 33, v12
	v_sub_u32_e32 v0, v53, v0
	v_add_u32_e32 v33, 11, v12
	v_add_u32_e32 v34, 27, v12
	s_and_b64 s[10:11], vcc, s[0:1]
	v_cmp_ge_u32_e32 vcc, v5, v31
	v_cmp_lt_u32_e64 s[0:1], v5, v32
	v_or_b32_e32 v31, 34, v12
	v_lshl_add_u32 v89, v0, 2, v13
	v_sub_u32_e32 v0, v53, v14
	v_cmp_ge_u32_e64 s[36:37], v5, v28
	v_cmp_ge_u32_e64 s[38:39], v5, v30
	v_cmp_ge_u32_e64 s[40:41], v5, v32
	s_and_b64 s[12:13], vcc, s[0:1]
	v_cmp_ge_u32_e32 vcc, v5, v33
	v_cmp_ge_u32_e64 s[42:43], v5, v34
	v_cmp_lt_u32_e64 s[0:1], v5, v34
	v_add_u32_e32 v5, 40, v12
	v_or_b32_e32 v35, 35, v12
	v_lshl_add_u32 v90, v0, 2, v13
	v_sub_u32_e32 v0, v53, v31
	s_and_b64 s[14:15], vcc, s[0:1]
	v_add_u32_e32 v29, 41, v12
	v_lshl_add_u32 v91, v0, 2, v13
	v_sub_u32_e32 v0, v53, v35
	v_cmp_ge_u32_e32 vcc, v8, v28
	v_cmp_lt_u32_e64 s[0:1], v8, v5
	v_cmp_ge_u32_e64 s[34:35], v53, v33
	v_add_u32_e32 v33, 42, v12
	v_lshl_add_u32 v92, v0, 2, v13
	s_and_b64 s[16:17], vcc, s[0:1]
	v_cmp_ge_u32_e32 vcc, v8, v30
	v_cmp_lt_u32_e64 s[0:1], v8, v29
	v_cmp_lt_u32_e64 s[30:31], v27, v5
	v_or_b32_e32 v0, 48, v12
	v_min_u32_e32 v5, 8, v12
	v_cmp_lt_u32_e64 s[46:47], v8, v30
	s_and_b64 s[18:19], vcc, s[0:1]
	v_cmp_ge_u32_e32 vcc, v8, v32
	v_cmp_lt_u32_e64 s[0:1], v8, v33
	v_cmp_lt_u32_e64 s[54:55], v27, v29
	v_add_u32_e32 v29, 40, v5
	v_add_u32_e32 v30, 56, v5
	v_mul_u32_u24_e32 v93, 0x410, v0
	v_or_b32_e32 v5, 49, v12
	v_sub_u32_e32 v0, v53, v0
	v_cmp_lt_u32_e64 s[50:51], v8, v34
	s_and_b64 s[20:21], vcc, s[0:1]
	v_cmp_ge_u32_e32 vcc, v8, v34
	v_or_b32_e32 v34, 50, v12
	v_lshl_add_u32 v94, v0, 2, v13
	v_sub_u32_e32 v0, v53, v5
	v_or_b32_e32 v18, v4, v53
	v_or_b32_e32 v38, 51, v12
	v_lshl_add_u32 v95, v0, 2, v13
	v_sub_u32_e32 v0, v53, v34
	v_add_u32_e32 v36, 43, v12
	s_add_i32 s24, 0, 0x12000
	v_mul_lo_u32 v18, v18, s26
	v_min_u32_e32 v31, 7, v12
	v_min_u32_e32 v35, 6, v12
	v_min_u32_e32 v12, 5, v12
	v_lshl_add_u32 v96, v0, 2, v13
	v_sub_u32_e32 v0, v53, v38
	v_add_u32_e32 v11, 0, v2
	v_cmp_lt_u32_e64 s[44:45], v8, v28
	v_cmp_lt_u32_e64 s[48:49], v8, v32
	v_cmp_lt_u32_e64 s[0:1], v8, v36
	v_add_u32_e32 v14, s24, v2
	v_add_u32_e32 v28, s24, v18
	v_add_u32_e32 v32, 41, v31
	v_add_u32_e32 v31, 57, v31
	v_add_u32_e32 v37, 42, v35
	v_add_u32_e32 v35, 58, v35
	v_add_u32_e32 v39, 43, v12
	v_add_u32_e32 v12, 59, v12
	v_lshl_add_u32 v97, v0, 2, v13
	v_or_b32_e32 v13, 64, v2
	v_or_b32_e32 v34, 0x80, v2
	v_or_b32_e32 v38, 0xc0, v2
	v_or_b32_e32 v40, 0x100, v2
	v_or_b32_e32 v41, 0x140, v2
	v_or_b32_e32 v42, 0x180, v2
	v_or_b32_e32 v43, 0x1c0, v2
	v_or_b32_e32 v44, 0x200, v2
	v_or_b32_e32 v45, 0x240, v2
	v_or_b32_e32 v68, 0x280, v2
	v_or_b32_e32 v69, 0x2c0, v2
	v_or_b32_e32 v128, 0x300, v2
	v_or_b32_e32 v129, 0x340, v2
	v_or_b32_e32 v142, 0x380, v2
	v_or_b32_e32 v143, 0x3c0, v2
	v_ashrrev_i32_e32 v5, 31, v4
	v_or_b32_e32 v99, 1, v57
	v_or_b32_e32 v101, 2, v57
	v_or_b32_e32 v103, 3, v57
	v_cmp_eq_u32_e64 s[4:5], 0, v53
	s_and_b64 s[0:1], vcc, s[0:1]
	v_lshl_add_u32 v98, v57, 2, s25
	v_lshl_add_u32 v100, v99, 2, s25
	v_lshl_add_u32 v102, v101, 2, s25
	v_lshl_add_u32 v104, v103, 2, s25
	v_lshlrev_b32_e32 v0, 1, v6
	v_add_u32_e32 v105, v3, v17
	v_add_u32_e32 v106, v3, v19
	v_add_u32_e32 v107, v3, v20
	v_add_u32_e32 v108, v3, v21
	v_add_u32_e32 v109, v3, v22
	v_add_u32_e32 v110, v3, v23
	v_add_u32_e32 v111, v3, v24
	v_add_u32_e32 v112, v3, v25
	v_add_u32_e32 v113, v7, v9
	v_add_u32_e32 v114, v11, v10
	v_add_u32_e32 v115, v11, v26
	v_add_u32_e32 v116, v14, v18
	v_add_u32_e32 v117, v28, v13
	v_add_u32_e32 v118, v28, v34
	v_add_u32_e32 v119, v28, v38
	v_add_u32_e32 v120, v28, v40
	v_add_u32_e32 v121, v28, v41
	v_add_u32_e32 v122, v28, v42
	v_add_u32_e32 v123, v28, v43
	v_add_u32_e32 v124, v28, v44
	v_add_u32_e32 v125, v28, v45
	v_add_u32_e32 v126, v28, v68
	v_add_u32_e32 v127, v28, v69
	v_add_u32_e32 v128, v28, v128
	v_add_u32_e32 v129, v28, v129
	v_add_u32_e32 v142, v28, v142
	v_add_u32_e32 v143, v28, v143
	v_lshlrev_b64 v[68:69], 1, v[4:5]
	v_add_u32_e32 v144, v15, v2
	v_add_u32_e32 v145, v16, v2
	v_cmp_lt_u32_e64 s[56:57], v27, v33
	v_cmp_lt_u32_e64 s[58:59], v27, v36
	v_cmp_ge_u32_e64 s[60:61], v8, v29
	v_cmp_ge_u32_e64 s[62:63], v8, v32
	v_cmp_ge_u32_e64 s[64:65], v8, v37
	v_cmp_ge_u32_e64 s[66:67], v8, v39
	v_cmp_lt_u32_e64 s[68:69], v27, v30
	v_cmp_lt_u32_e64 s[70:71], v27, v31
	v_cmp_lt_u32_e64 s[72:73], v27, v35
	v_cmp_lt_u32_e64 s[74:75], v27, v12
	s_branch .LBB0_149

; __device__ __forceinline__ int otid() { int t = threadIdx.x; asm volatile("" : "+v"(t)); return t; }
; __device__ __forceinline__ void na_phase(const Params& p, int l, unsigned char* shm, int item_lo, int item_hi, int wg, int nwg) {
;     bf16_t* Z = (bf16_t*)(p.ws + WS_Z);
;     const float* rpb = p.in[3] + (size_t)l * 8 * 15 * 31;
;     const int tid = otid(), w = tid >> 6, lane = tid & 63, n_ = lane & 15, kg = lane >> 4;
;     unsigned char* Ks = shm;
;     unsigned char* Vt = shm + 73728;
;     float* red = (float*)(shm + 140288);
;     float* brow = red + 512;
;     for (int item = item_lo + wg; item < item_hi; item += nwg) {
;         const int h = item & 7, i = (item >> 3) & 255, b = item >> 11;
;         const int s0 = min(max(i - 4, 0), 248);
;         bf16x8 qf[4][2];
; #pragma unroll
;         for (int mt = 0; mt < 4; ++mt)
; #pragma unroll
;             for (int ks = 0; ks < 2; ++ks) qf[mt][ks] = *(const bf16x8*)(Z + (size_t)(b * T + i * 64 + 16 * mt + n_) * ZLD + ZC_NAQ + h * 64 + 32 * ks + 8 * kg);
; #pragma unroll
;         for (int it = 0; it < 8; ++it) { const int idx = it * NTHR + tid, key = idx >> 3, ch = idx & 7;
;             const size_t tok = (size_t)b * T + (size_t)(s0 + (key >> 6)) * 64 + (key & 63);
;             *(u32x4*)(Ks + key * 144 + ch * 16) = *(const u32x4*)(Z + tok * ZLD + ZC_NAK + h * 64 + ch * 8); }
;         { const size_t tok = (size_t)b * T + (size_t)(s0 + (tid >> 6)) * 64 + (tid & 63);
; #pragma unroll
;           for (int it = 0; it < 8; ++it) { const u32x4 v4 = *(const u32x4*)(Z + tok * ZLD + ZC_NAV + h * 64 + it * 8); const unsigned vv[4] = {v4.x, v4.y, v4.z, v4.w};
; #pragma unroll
;               for (int e = 0; e < 4; ++e) { *(bf16_t*)(Vt + (it * 8 + 2 * e) * 1040 + tid * 2) = (bf16_t)(vv[e] & 0xffffu); *(bf16_t*)(Vt + (it * 8 + 2 * e + 1) * 1040 + tid * 2) = (bf16_t)(vv[e] >> 16); } } }
;         if (lane < 31) brow[w * 32 + lane] = rpb[(size_t)h * 15 * 31 + (size_t)(s0 + w - i + 7) * 31 + lane];
.LBB0_355:
	s_or_b64 exec, exec, s[0:1]
	v_readlane_b32 s23, v253, 0
	s_waitcnt vmcnt(0) lgkmcnt(0)
	s_barrier
	v_mov_b32_e32 v5, v160
	s_cmpk_gt_i32 s23, 0x1ff
	s_cbranch_scc1 .LBB0_505
	v_readlane_b32 s4, v254, 9
	v_ashrrev_i32_e32 v47, 6, v5
	v_and_b32_e32 v2, 48, v5
	v_mov_b32_e32 v3, v1
	v_and_b32_e32 v0, 7, v5
	v_readlane_b32 s6, v254, 11
	v_readlane_b32 s7, v254, 12
	v_readlane_b32 s8, v254, 13
	v_readlane_b32 s9, v254, 14
	v_bfe_u32 v8, v5, 4, 2
	v_lshl_add_u64 v[48:49], s[78:79], 0, v[2:3]
	v_lshlrev_b32_e32 v6, 3, v0
	v_lshl_add_u32 v3, v0, 4, 0
	v_and_b32_e32 v0, 3, v47
	v_and_b32_e32 v53, 15, v5
	v_lshlrev_b32_e32 v12, 2, v8
	v_cmp_ne_u32_e64 s[6:7], 0, v0
	v_cmp_ne_u32_e64 s[8:9], 3, v0
	v_lshlrev_b32_e32 v0, 4, v0
	v_or_b32_e32 v4, v0, v53
	v_or_b32_e32 v57, v0, v12
	v_lshlrev_b32_e32 v0, 1, v53
	v_lshl_add_u64 v[50:51], s[78:79], 0, v[0:1]
	v_add_u32_e32 v0, 0x200, v5
	v_ashrrev_i32_e32 v19, 3, v0
	v_ashrrev_i32_e32 v61, 9, v0
	v_add_u32_e32 v0, 0x400, v5
	v_ashrrev_i32_e32 v20, 3, v0
	v_ashrrev_i32_e32 v63, 9, v0
	v_add_u32_e32 v0, 0x600, v5
	s_mul_i32 s1, s46, 0x3a20
	v_readlane_b32 s10, v254, 15
	v_ashrrev_i32_e32 v21, 3, v0
	v_ashrrev_i32_e32 v65, 9, v0
	v_add_u32_e32 v0, 0x800, v5
	s_mul_hi_i32 s0, s46, 0x3a20
	v_readlane_b32 s11, v254, 16
	s_add_u32 s2, s10, s1
	v_ashrrev_i32_e32 v22, 3, v0
	v_ashrrev_i32_e32 v67, 9, v0
	v_add_u32_e32 v0, 0xa00, v5
	s_addc_u32 s3, s11, s0
	v_ashrrev_i32_e32 v23, 3, v0
	v_ashrrev_i32_e32 v70, 9, v0
	v_add_u32_e32 v0, 0xc00, v5
	v_readlane_b32 s5, v254, 10
	v_readlane_b32 s12, v254, 17
	v_readlane_b32 s13, v254, 18
	v_readlane_b32 s14, v254, 19
	v_readlane_b32 s15, v254, 20
	v_readlane_b32 s16, v254, 21
	v_readlane_b32 s17, v254, 22
	v_readlane_b32 s18, v254, 23
	v_readlane_b32 s19, v254, 24
	v_writelane_b32 v254, s2, 39
	v_and_b32_e32 v46, 63, v5
	v_readlane_b32 s0, v253, 42
	v_lshlrev_b32_e32 v9, 7, v47
	v_ashrrev_i32_e32 v24, 3, v0
	v_ashrrev_i32_e32 v71, 9, v0
	v_add_u32_e32 v0, 0xe00, v5
	v_writelane_b32 v254, s3, 40
	v_lshl_add_u32 v7, v46, 2, s0
	v_lshlrev_b32_e32 v55, 1, v5
	v_cmp_gt_u32_e64 s[2:3], 31, v46
	v_and_b32_e32 v10, 0xfffffcf, v5
	v_add_u32_e32 v13, s0, v9
	v_and_b32_e32 v14, 0xffffffc0, v5
	s_movk_i32 s26, 0x410
	v_ashrrev_i32_e32 v17, 3, v5
	v_ashrrev_i32_e32 v59, 9, v5
	s_movk_i32 s0, 0x90
	v_ashrrev_i32_e32 v25, 3, v0
	v_ashrrev_i32_e32 v72, 9, v0
	v_or_b32_e32 v0, 48, v5
	v_sub_u32_e64 v5, v12, 8 clamp
	v_writelane_b32 v254, s2, 41
	v_mad_u32_u24 v16, v4, s26, 0
	v_and_b32_e32 v4, 0xffffffe0, v17
	v_and_b32_e32 v52, 63, v17
	v_mul_lo_u32 v17, v17, s0
	v_and_b32_e32 v54, 63, v19
	v_mul_lo_u32 v19, v19, s0
	v_and_b32_e32 v56, 63, v20
	v_mul_lo_u32 v20, v20, s0
	v_and_b32_e32 v58, 63, v21
	v_mul_lo_u32 v21, v21, s0
	v_and_b32_e32 v60, 63, v22
	v_mul_lo_u32 v22, v22, s0
	v_and_b32_e32 v62, 63, v23
	v_mul_lo_u32 v23, v23, s0
	v_and_b32_e32 v64, 63, v24
	v_mul_lo_u32 v24, v24, s0
	v_and_b32_e32 v66, 63, v25
	v_mul_lo_u32 v25, v25, s0
	v_mul_lo_u32 v10, v10, s0
	v_mul_lo_u32 v26, v0, s0
	v_cmp_ge_u32_e64 s[0:1], v53, v5
	v_sub_u32_e32 v5, v53, v12
	v_writelane_b32 v254, s3, 42
	v_lshl_add_u32 v74, v5, 2, v13
	v_or_b32_e32 v5, 1, v12
	v_writelane_b32 v254, s0, 43
	v_sub_u32_e64 v27, v5, 8 clamp
	v_mul_u32_u24_e32 v75, 0x1040, v8
	v_writelane_b32 v254, s1, 44
	v_max_u32_e32 v8, 8, v5
	v_cmp_ge_u32_e64 s[0:1], v53, v27
	v_sub_u32_e32 v27, v53, v5
	v_mul_u32_u24_e32 v77, 0x410, v5
	v_or_b32_e32 v5, 2, v12
	v_writelane_b32 v254, s0, 45
	v_lshl_add_u32 v76, v27, 2, v13
	v_max_u32_e32 v27, 8, v5
	v_sub_u32_e64 v28, v5, 8 clamp
	v_sub_u32_e32 v5, v53, v5
	v_writelane_b32 v254, s1, 46
	v_cmp_ge_u32_e64 s[0:1], v53, v28
	v_lshl_add_u32 v78, v5, 2, v13
	v_or_b32_e32 v5, 3, v12
	v_and_b32_e32 v0, 0xffffff9e, v55
	v_writelane_b32 v254, s0, 47
	v_sub_u32_e64 v29, v5, 8 clamp
	v_add_u32_e32 v73, 0, v0
	v_max_u32_e32 v0, 8, v12
	v_writelane_b32 v254, s1, 48
	v_max_u32_e32 v28, 8, v5
	v_cmp_ge_u32_e64 s[0:1], v53, v29
	v_sub_u32_e32 v5, v53, v5
	v_add_u32_e32 v0, 8, v0
	v_writelane_b32 v254, s0, 49
	v_lshl_add_u32 v79, v5, 2, v13
	v_or_b32_e32 v5, 16, v53
	v_writelane_b32 v254, s1, 50
	v_cmp_lt_u32_e64 s[0:1], v5, v0
	v_add_u32_e32 v8, 8, v8
	v_add_u32_e32 v27, 8, v27
	v_writelane_b32 v254, s0, 51
	v_add_u32_e32 v28, 8, v28
	v_or_b32_e32 v29, v5, v14
	v_writelane_b32 v254, s1, 52
	v_cmp_lt_u32_e64 s[0:1], v5, v8
	v_or_b32_e32 v8, 32, v53
	v_or_b32_e32 v0, v8, v14
	v_writelane_b32 v254, s0, 53
	v_lshl_add_u32 v81, v0, 1, 0
	v_readlane_b32 s25, v253, 43
	v_writelane_b32 v254, s1, 54
	v_cmp_lt_u32_e64 s[0:1], v5, v27
	v_or_b32_e32 v27, 48, v53
	v_or_b32_e32 v0, v27, v14
	v_writelane_b32 v254, s0, 55
	v_lshl_add_u32 v82, v0, 1, 0
	v_or_b32_e32 v0, 16, v12
	v_lshl_add_u32 v80, v29, 1, 0
	v_writelane_b32 v254, s1, 56
	v_cmp_lt_u32_e64 s[0:1], v5, v28
	v_sub_u32_e32 v29, v53, v0
	v_mul_u32_u24_e32 v84, 0x410, v0
	v_or_b32_e32 v0, 17, v12
	v_lshl_add_u32 v15, v14, 2, s25
	v_writelane_b32 v254, s0, 57
	v_add_u32_e32 v14, 8, v12
	v_sub_u32_e32 v0, v53, v0
	v_writelane_b32 v254, s1, 58
	v_cmp_ge_u32_e64 s[0:1], v53, v14
	v_lshl_add_u32 v85, v0, 2, v13
	v_or_b32_e32 v0, 18, v12
	v_writelane_b32 v254, s0, 59
	v_lshl_add_u32 v83, v29, 2, v13
	v_add_u32_e32 v29, 9, v12
	v_sub_u32_e32 v0, v53, v0
	v_writelane_b32 v254, s1, 60
	v_cmp_ge_u32_e64 s[0:1], v53, v29
	v_lshl_add_u32 v86, v0, 2, v13
	v_or_b32_e32 v0, 19, v12
	v_add_u32_e32 v28, 24, v12
	v_writelane_b32 v254, s0, 61
	v_sub_u32_e32 v0, v53, v0
	v_add_u32_e32 v30, 25, v12
	v_writelane_b32 v254, s1, 62
	v_lshl_add_u32 v87, v0, 2, v13
	v_cmp_ge_u32_e32 vcc, v5, v14
	v_cmp_lt_u32_e64 s[0:1], v5, v28
	v_or_b32_e32 v0, 32, v12
	v_add_u32_e32 v31, 10, v12
; __device__ __forceinline__ int otid() { int t = threadIdx.x; asm volatile("" : "+v"(t)); return t; }
; __device__ __forceinline__ void na_phase(const Params& p, int l, unsigned char* shm, int item_lo, int item_hi, int wg, int nwg) {
;     ...
;     const int tid = otid(), w = tid >> 6, lane = tid & 63, n_ = lane & 15, kg = lane >> 4;
;     unsigned char* Ks = shm;
;     unsigned char* Vt = shm + 73728;
;     float* red = (float*)(shm + 140288);
;     float* brow = red + 512;
;     for (int item = item_lo + wg; item < item_hi; item += nwg) {
;         const int h = item & 7, i = (item >> 3) & 255, b = item >> 11;
;         const int s0 = min(max(i - 4, 0), 248);
;         bf16x8 qf[4][2];
; #pragma unroll
;         for (int mt = 0; mt < 4; ++mt)
; #pragma unroll
;             for (int ks = 0; ks < 2; ++ks) qf[mt][ks] = *(const bf16x8*)(Z + (size_t)(b * T + i * 64 + 16 * mt + n_) * ZLD + ZC_NAQ + h * 64 + 32 * ks + 8 * kg);
; #pragma unroll
;         for (int it = 0; it < 8; ++it) { const int idx = it * NTHR + tid, key = idx >> 3, ch = idx & 7;
;             const size_t tok = (size_t)b * T + (size_t)(s0 + (key >> 6)) * 64 + (key & 63);
;             *(u32x4*)(Ks + key * 144 + ch * 16) = *(const u32x4*)(Z + tok * ZLD + ZC_NAK + h * 64 + ch * 8); }
;         { const size_t tok = (size_t)b * T + (size_t)(s0 + (tid >> 6)) * 64 + (tid & 63);
; #pragma unroll
;           for (int it = 0; it < 8; ++it) { const u32x4 v4 = *(const u32x4*)(Z + tok * ZLD + ZC_NAV + h * 64 + it * 8); const unsigned vv[4] = {v4.x, v4.y, v4.z, v4.w};
; #pragma unroll
;               for (int e = 0; e < 4; ++e) { *(bf16_t*)(Vt + (it * 8 + 2 * e) * 1040 + tid * 2) = (bf16_t)(vv[e] & 0xffffu); *(bf16_t*)(Vt + (it * 8 + 2 * e + 1) * 1040 + tid * 2) = (bf16_t)(vv[e] >> 16); } } }
;         if (lane < 31) brow[w * 32 + lane] = rpb[(size_t)h * 15 * 31 + (size_t)(s0 + w - i + 7) * 31 + lane];
;     ...
;                 for (int i2 = 0; i2 < 4; ++i2) { const int q = 16 * mt + 4 * kg + i2, col = 16 * nt + n_, cs = min(max(q - 8, 0), 48); const bool ok = (col >= cs) && (col < cs + 16);
;                     const float s = acc[mt][nt][i2] * 0.125f + brow[w * 32 + (ok ? col - q + 15 : 0)];
	s_and_b64 s[2:3], vcc, s[0:1]
	v_cmp_ge_u32_e32 vcc, v5, v29
	v_cmp_lt_u32_e64 s[0:1], v5, v30
	v_mul_u32_u24_e32 v88, 0x410, v0
	v_or_b32_e32 v14, 33, v12
	v_sub_u32_e32 v0, v53, v0
	v_cmp_ge_u32_e64 s[30:31], v53, v31
	v_add_u32_e32 v32, 26, v12
	s_and_b64 s[10:11], vcc, s[0:1]
	v_cmp_ge_u32_e32 vcc, v5, v31
	v_or_b32_e32 v31, 34, v12
	v_lshl_add_u32 v89, v0, 2, v13
	v_sub_u32_e32 v0, v53, v14
	v_add_u32_e32 v33, 11, v12
	v_add_u32_e32 v34, 27, v12
	v_cmp_lt_u32_e64 s[0:1], v5, v32
	v_or_b32_e32 v35, 35, v12
	v_lshl_add_u32 v90, v0, 2, v13
	v_sub_u32_e32 v0, v53, v31
	v_cmp_ge_u32_e64 s[36:37], v5, v28
	v_cmp_ge_u32_e64 s[38:39], v5, v30
	v_cmp_ge_u32_e64 s[40:41], v5, v32
	s_and_b64 s[12:13], vcc, s[0:1]
	v_cmp_ge_u32_e32 vcc, v5, v33
	v_cmp_ge_u32_e64 s[42:43], v5, v34
	v_cmp_lt_u32_e64 s[0:1], v5, v34
	v_add_u32_e32 v5, 40, v12
	v_lshl_add_u32 v91, v0, 2, v13
	v_sub_u32_e32 v0, v53, v35
	s_and_b64 s[14:15], vcc, s[0:1]
	v_add_u32_e32 v29, 41, v12
	v_lshl_add_u32 v92, v0, 2, v13
	v_cmp_ge_u32_e32 vcc, v8, v28
	v_cmp_lt_u32_e64 s[0:1], v8, v5
	v_cmp_lt_u32_e64 s[52:53], v27, v5
	v_or_b32_e32 v0, 48, v12
	v_min_u32_e32 v5, 8, v12
	v_cmp_ge_u32_e64 s[34:35], v53, v33
	v_cmp_lt_u32_e64 s[44:45], v8, v28
	v_add_u32_e32 v33, 42, v12
	s_and_b64 s[16:17], vcc, s[0:1]
	v_cmp_ge_u32_e32 vcc, v8, v30
	v_cmp_lt_u32_e64 s[0:1], v8, v29
	v_add_u32_e32 v14, 40, v5
	v_add_u32_e32 v28, 56, v5
	v_mul_u32_u24_e32 v93, 0x410, v0
	v_or_b32_e32 v5, 49, v12
	v_sub_u32_e32 v0, v53, v0
	s_and_b64 s[18:19], vcc, s[0:1]
	v_cmp_ge_u32_e32 vcc, v8, v32
	v_cmp_lt_u32_e64 s[0:1], v8, v33
	v_or_b32_e32 v31, 50, v12
	v_lshl_add_u32 v94, v0, 2, v13
	v_sub_u32_e32 v0, v53, v5
	v_or_b32_e32 v18, v4, v53
	v_cmp_lt_u32_e64 s[50:51], v8, v34
	s_and_b64 s[20:21], vcc, s[0:1]
	v_cmp_ge_u32_e32 vcc, v8, v34
	v_or_b32_e32 v34, 51, v12
	v_lshl_add_u32 v95, v0, 2, v13
	v_sub_u32_e32 v0, v53, v31
	v_cmp_lt_u32_e64 s[48:49], v8, v32
	v_add_u32_e32 v36, 43, v12
	v_cmp_lt_u32_e64 s[54:55], v27, v29
	v_min_u32_e32 v29, 7, v12
	v_min_u32_e32 v32, 6, v12
	v_min_u32_e32 v12, 5, v12
	v_lshl_add_u32 v96, v0, 2, v13
	v_sub_u32_e32 v0, v53, v34
	s_add_i32 s24, 0, 0x12000
	v_mul_lo_u32 v18, v18, s26
	v_add_u32_e32 v11, 0, v2
	v_cmp_lt_u32_e64 s[46:47], v8, v30
	v_cmp_lt_u32_e64 s[0:1], v8, v36
	v_cmp_lt_u32_e64 s[56:57], v27, v33
	v_add_u32_e32 v30, 41, v29
	v_add_u32_e32 v29, 57, v29
	v_add_u32_e32 v33, 42, v32
	v_add_u32_e32 v32, 58, v32
	v_add_u32_e32 v35, 43, v12
	v_add_u32_e32 v12, 59, v12
	v_lshl_add_u32 v97, v0, 2, v13
	v_add_u32_e32 v13, s24, v2
	v_or_b32_e32 v31, 64, v2
	v_add_u32_e32 v34, s24, v18
	v_or_b32_e32 v37, 0x80, v2
	v_or_b32_e32 v38, 0xc0, v2
	v_or_b32_e32 v39, 0x100, v2
	v_or_b32_e32 v40, 0x140, v2
	v_or_b32_e32 v41, 0x180, v2
	v_or_b32_e32 v42, 0x1c0, v2
	v_or_b32_e32 v43, 0x200, v2
	v_or_b32_e32 v44, 0x240, v2
	v_or_b32_e32 v45, 0x280, v2
	v_or_b32_e32 v68, 0x2c0, v2
	v_or_b32_e32 v69, 0x300, v2
	v_or_b32_e32 v129, 0x340, v2
	v_or_b32_e32 v142, 0x380, v2
	v_or_b32_e32 v143, 0x3c0, v2
	v_ashrrev_i32_e32 v5, 31, v4
	v_or_b32_e32 v99, 1, v57
	v_or_b32_e32 v101, 2, v57
	v_or_b32_e32 v103, 3, v57
	v_cmp_eq_u32_e64 s[4:5], 0, v53
	s_and_b64 s[0:1], vcc, s[0:1]
	v_lshl_add_u32 v98, v57, 2, s25
	v_lshl_add_u32 v100, v99, 2, s25
	v_lshl_add_u32 v102, v101, 2, s25
	v_lshl_add_u32 v104, v103, 2, s25
	v_lshlrev_b32_e32 v0, 1, v6
	v_add_u32_e32 v105, v3, v17
	v_add_u32_e32 v106, v3, v19
	v_add_u32_e32 v107, v3, v20
	v_add_u32_e32 v108, v3, v21
	v_add_u32_e32 v109, v3, v22
	v_add_u32_e32 v110, v3, v23
	v_add_u32_e32 v111, v3, v24
	v_add_u32_e32 v112, v3, v25
	v_add_u32_e32 v113, v7, v9
	v_add_u32_e32 v114, v11, v10
	v_add_u32_e32 v115, v11, v26
	v_add_u32_e32 v116, v13, v18
	v_add_u32_e32 v117, v34, v31
	v_add_u32_e32 v118, v34, v37
	v_add_u32_e32 v119, v34, v38
	v_add_u32_e32 v120, v34, v39
	v_add_u32_e32 v121, v34, v40
	v_add_u32_e32 v122, v34, v41
	v_add_u32_e32 v123, v34, v42
	v_add_u32_e32 v124, v34, v43
	v_add_u32_e32 v125, v34, v44
	v_add_u32_e32 v126, v34, v45
	v_add_u32_e32 v127, v34, v68
	v_add_u32_e32 v128, v34, v69
	v_add_u32_e32 v129, v34, v129
	v_add_u32_e32 v142, v34, v142
	v_add_u32_e32 v143, v34, v143
	v_lshlrev_b64 v[68:69], 1, v[4:5]
	v_add_u32_e32 v144, v15, v2
	v_add_u32_e32 v145, v16, v2
	v_cmp_lt_u32_e64 s[58:59], v27, v36
	v_cmp_ge_u32_e64 s[60:61], v8, v14
	v_cmp_ge_u32_e64 s[62:63], v8, v30
	v_cmp_ge_u32_e64 s[64:65], v8, v33
	v_cmp_ge_u32_e64 s[66:67], v8, v35
	v_cmp_lt_u32_e64 s[68:69], v27, v28
	v_cmp_lt_u32_e64 s[70:71], v27, v29
	v_cmp_lt_u32_e64 s[72:73], v27, v32
	v_cmp_lt_u32_e64 s[74:75], v27, v12
	s_branch .LBB0_358
; __device__ __forceinline__ bf16_t f2bf(float f) { return (bf16_t)(cvt_pk_bf16(f, 0.f) & 0xffffu); }
; __device__ __forceinline__ void na_phase(const Params& p, int l, unsigned char* shm, int item_lo, int item_hi, int wg, int nwg) {
;     ...
;             for (int i2 = 0; i2 < 4; ++i2) { const int q = 16 * qt + 4 * kg + i2; float tot = 0.f;
; #pragma unroll
;                 for (int ww = 0; ww < 8; ++ww) tot += red[ww * 64 + q];
;                 const float inv = 1.0f / tot;
; #pragma unroll
;                 for (int j = 0; j < 2; ++j) Z[(size_t)(b * T + i * 64 + q) * ZLD + ZC_NAQ + h * 64 + 16 * (2 * dp + j) + n_] = f2bf(o2[j][i2] * inv); }
;         }
;         __syncthreads();
.LBB0_357:
	s_or_b64 exec, exec, vcc
	ds_read2st64_b32 v[12:13], v98 offset1:1
	s_lshl_b32 s25, s25, 6
	s_lshl_b32 s76, s25, 1
	v_lshl_add_u64 v[10:11], v[50:51], 0, s[76:77]
	s_add_i32 s23, s23, s28
	s_waitcnt lgkmcnt(0)
	v_add_f32_e32 v12, 0, v12
	v_add_f32_e32 v14, v12, v13
	ds_read2st64_b32 v[12:13], v98 offset0:2 offset1:3
	s_cmpk_lt_i32 s23, 0x200
	s_waitcnt lgkmcnt(0)
	v_add_f32_e32 v12, v14, v12
	v_add_f32_e32 v14, v12, v13
	ds_read2st64_b32 v[12:13], v98 offset0:4 offset1:5
	s_waitcnt lgkmcnt(0)
	v_add_f32_e32 v12, v14, v12
	v_add_f32_e32 v14, v12, v13
	ds_read2st64_b32 v[12:13], v98 offset0:6 offset1:7
	s_waitcnt lgkmcnt(0)
	v_add_f32_e32 v12, v14, v12
	v_add_f32_e32 v12, v12, v13
	v_div_scale_f32 v13, s[26:27], v12, v12, 1.0
	v_rcp_f32_e32 v14, v13
	s_nop 0
	v_fma_f32 v15, -v13, v14, 1.0
	v_fmac_f32_e32 v14, v15, v14
	v_div_scale_f32 v15, vcc, 1.0, v12, 1.0
	v_mul_f32_e32 v16, v15, v14
	v_fma_f32 v17, -v13, v16, v15
	v_fmac_f32_e32 v16, v17, v14
	v_fma_f32 v13, -v13, v16, v15
	v_div_fmas_f32 v13, v13, v14, v16
	v_div_fixup_f32 v14, v13, v12, 1.0
	v_or_b32_e32 v12, s24, v57
	v_mad_i64_i32 v[12:13], s[26:27], v12, s22, v[10:11]
	v_mul_f32_e32 v6, v6, v14
	v_lshl_add_u64 v[12:13], v[12:13], 0, v[68:69]
	v_mul_f32_e32 v2, v2, v14
	v_cvt_pk_bf16_f32 v6, v6, v1
	global_store_short v[12:13], v6, off
	v_cvt_pk_bf16_f32 v2, v2, v1
	global_store_short v[12:13], v2, off offset:32
	ds_read2st64_b32 v[12:13], v100 offset1:1
	s_waitcnt lgkmcnt(0)
	v_add_f32_e32 v2, 0, v12
	v_add_f32_e32 v2, v2, v13
	ds_read2st64_b32 v[12:13], v100 offset0:2 offset1:3
	s_waitcnt lgkmcnt(0)
	v_add_f32_e32 v2, v2, v12
	v_add_f32_e32 v2, v2, v13
	ds_read2st64_b32 v[12:13], v100 offset0:4 offset1:5
	s_waitcnt lgkmcnt(0)
	v_add_f32_e32 v2, v2, v12
	v_add_f32_e32 v2, v2, v13
	ds_read2st64_b32 v[12:13], v100 offset0:6 offset1:7
	s_waitcnt lgkmcnt(0)
	v_add_f32_e32 v2, v2, v12
	v_add_f32_e32 v2, v2, v13
	v_div_scale_f32 v6, s[26:27], v2, v2, 1.0
	v_rcp_f32_e32 v12, v6
	s_nop 0
	v_fma_f32 v13, -v6, v12, 1.0
	v_fmac_f32_e32 v12, v13, v12
	v_div_scale_f32 v13, vcc, 1.0, v2, 1.0
	v_mul_f32_e32 v14, v13, v12
	v_fma_f32 v15, -v6, v14, v13
	v_fmac_f32_e32 v14, v15, v12
	v_fma_f32 v6, -v6, v14, v13
	v_div_fmas_f32 v6, v6, v12, v14
	v_div_fixup_f32 v2, v6, v2, 1.0
	v_or_b32_e32 v6, s24, v99
	v_mad_i64_i32 v[12:13], s[26:27], v6, s22, v[10:11]
	v_mul_f32_e32 v6, v7, v2
	v_mul_f32_e32 v2, v3, v2
	v_cvt_pk_bf16_f32 v14, v6, v1
	v_lshl_add_u64 v[6:7], v[12:13], 0, v[68:69]
	v_cvt_pk_bf16_f32 v2, v2, v1
	global_store_short v[6:7], v2, off offset:32
	ds_read2st64_b32 v[2:3], v102 offset1:1
	global_store_short v[6:7], v14, off
	s_waitcnt lgkmcnt(0)
	v_add_f32_e32 v2, 0, v2
	v_add_f32_e32 v6, v2, v3
	ds_read2st64_b32 v[2:3], v102 offset0:2 offset1:3
	s_waitcnt lgkmcnt(0)
	v_add_f32_e32 v2, v6, v2
	v_add_f32_e32 v6, v2, v3
	ds_read2st64_b32 v[2:3], v102 offset0:4 offset1:5
	s_waitcnt lgkmcnt(0)
	v_add_f32_e32 v2, v6, v2
	v_add_f32_e32 v6, v2, v3
	ds_read2st64_b32 v[2:3], v102 offset0:6 offset1:7
	s_waitcnt lgkmcnt(0)
	v_add_f32_e32 v2, v6, v2
	v_add_f32_e32 v2, v2, v3
	v_div_scale_f32 v3, s[26:27], v2, v2, 1.0
	v_rcp_f32_e32 v6, v3
	s_nop 0
	v_fma_f32 v7, -v3, v6, 1.0
	v_fmac_f32_e32 v6, v7, v6
	v_div_scale_f32 v7, vcc, 1.0, v2, 1.0
	v_mul_f32_e32 v12, v7, v6
	v_fma_f32 v13, -v3, v12, v7
	v_fmac_f32_e32 v12, v13, v6
	v_fma_f32 v3, -v3, v12, v7
	v_div_fmas_f32 v3, v3, v6, v12
	v_div_fixup_f32 v6, v3, v2, 1.0
	v_or_b32_e32 v2, s24, v101
	v_mad_i64_i32 v[2:3], s[26:27], v2, s22, v[10:11]
	v_mul_f32_e32 v7, v8, v6
	v_lshl_add_u64 v[2:3], v[2:3], 0, v[68:69]
	v_mul_f32_e32 v4, v4, v6
	v_cvt_pk_bf16_f32 v7, v7, v1
	global_store_short v[2:3], v7, off
	v_cvt_pk_bf16_f32 v4, v4, v1
	global_store_short v[2:3], v4, off offset:32
	ds_read2st64_b32 v[2:3], v104 offset1:1
	s_waitcnt lgkmcnt(0)
	v_add_f32_e32 v2, 0, v2
	v_add_f32_e32 v4, v2, v3
	ds_read2st64_b32 v[2:3], v104 offset0:2 offset1:3
	s_waitcnt lgkmcnt(0)
	v_add_f32_e32 v2, v4, v2
	v_add_f32_e32 v4, v2, v3
	ds_read2st64_b32 v[2:3], v104 offset0:4 offset1:5
	s_waitcnt lgkmcnt(0)
	v_add_f32_e32 v2, v4, v2
	v_add_f32_e32 v4, v2, v3
	ds_read2st64_b32 v[2:3], v104 offset0:6 offset1:7
	s_waitcnt lgkmcnt(0)
	v_add_f32_e32 v2, v4, v2
	v_add_f32_e32 v2, v2, v3
	v_div_scale_f32 v3, s[26:27], v2, v2, 1.0
	v_rcp_f32_e32 v4, v3
	s_nop 0
	v_fma_f32 v6, -v3, v4, 1.0
	v_fmac_f32_e32 v4, v6, v4
	v_div_scale_f32 v6, vcc, 1.0, v2, 1.0
	v_mul_f32_e32 v7, v6, v4
	v_fma_f32 v8, -v3, v7, v6
	v_fmac_f32_e32 v7, v8, v4
	v_fma_f32 v3, -v3, v7, v6
	v_div_fmas_f32 v3, v3, v4, v7
	v_div_fixup_f32 v4, v3, v2, 1.0
	v_or_b32_e32 v2, s24, v103
	v_mad_i64_i32 v[2:3], s[24:25], v2, s22, v[10:11]
	v_mul_f32_e32 v6, v9, v4
	v_lshl_add_u64 v[2:3], v[2:3], 0, v[68:69]
	v_mul_f32_e32 v4, v5, v4
	v_cvt_pk_bf16_f32 v6, v6, v1
	global_store_short v[2:3], v6, off
	v_cvt_pk_bf16_f32 v4, v4, v1
	global_store_short v[2:3], v4, off offset:32
	s_barrier
	s_cbranch_scc0 .LBB0_504
